# speedup vs baseline: 1.0053x; 1.0053x over previous
; __device__ __forceinline__ unsigned cvt_pk_bf16(float lo, float hi) { unsigned r; asm volatile("v_cvt_pk_bf16_f32 %0, %1, %2" : "=v"(r) : "v"(lo), "v"(hi)); return r; }
; #define GAS __attribute__((address_space(1)))
;     __device__ __forceinline__ void operator()(const f32x4 (&acc)[2][2][4][2], const Unit& u, int wr, int wc, int fr, int fq) const {
;         const int row0 = u.pm * 256 + wr * 64 + fr; const int col0 = u.pn * 256 + wc * 32 + 8 * fq;
; #pragma unroll
;         for (int ai = 0; ai < 2; ++ai) {
;             u32x4 xo[4][2];
; #pragma unroll
;             for (int m = 0; m < 4; ++m)
; #pragma unroll
;                 for (int bj = 0; bj < 2; ++bj) xo[m][bj] = *(const GAS u32x4*)(xb + (size_t)(row0 + ai * 128 + m * 16) * DM + col0 + bj * 128);
;             asm volatile("" ::: "memory");
; #pragma unroll
;             for (int m = 0; m < 4; ++m) {
;                 const int row = row0 + ai * 128 + m * 16; float part = 0.f;
; #pragma unroll
;                 for (int bj = 0; bj < 2; ++bj) {
;                     bf16_t* xp = xb + (size_t)row * DM + col0 + bj * 128;
;                     const u32x4 q = xo[m][bj];
;                     f32x4 x0, x1;
;                     x0[0] = __uint_as_float(q.x << 16); x0[1] = __uint_as_float(q.x & 0xffff0000u); x0[2] = __uint_as_float(q.y << 16); x0[3] = __uint_as_float(q.y & 0xffff0000u);
;                     x1[0] = __uint_as_float(q.z << 16); x1[1] = __uint_as_float(q.z & 0xffff0000u); x1[2] = __uint_as_float(q.w << 16); x1[3] = __uint_as_float(q.w & 0xffff0000u);
;                     x0 = x0 + acc[ai][bj][m][0]; x1 = x1 + acc[ai][bj][m][1];
;                     part += (x0[0] * x0[0] + x0[1] * x0[1]) + (x0[2] * x0[2] + x0[3] * x0[3]) + (x1[0] * x1[0] + x1[1] * x1[1]) + (x1[2] * x1[2] + x1[3] * x1[3]);
;                     u32x4 w; w.x = cvt_pk_bf16(x0[0], x0[1]); w.y = cvt_pk_bf16(x0[2], x0[3]); w.z = cvt_pk_bf16(x1[0], x1[1]); w.w = cvt_pk_bf16(x1[2], x1[3]);
;                     *(GAS u32x4*)xp = w;
;                 }
;                 part += __shfl_xor(part, 16); part += __shfl_xor(part, 32);
;                 if (fq == 0) *(GAS float*)(ssacc + (size_t)row * 16 + u.pn * 4 + wc) = part;
.LBB0_197:
	v_lshl_or_b32 v162, s90, 8, v182
	v_lshl_add_u32 v166, s57, 8, v180
	v_ashrrev_i32_e32 v163, 31, v162
	v_lshlrev_b64 v[192:193], 1, v[162:163]
	v_ashrrev_i32_e32 v167, 31, v166
	v_lshl_add_u64 v[164:165], s[28:29], 0, v[192:193]
	v_lshlrev_b64 v[194:195], 11, v[166:167]
	v_lshl_add_u64 v[112:113], v[164:165], 0, v[194:195]
	global_load_dwordx4 v[184:187], v[112:113], off
	global_load_dwordx4 v[188:191], v[112:113], off offset:256
	v_or_b32_e32 v174, 16, v166
	v_ashrrev_i32_e32 v175, 31, v174
	v_or_b32_e32 v170, 32, v166
	v_lshlrev_b64 v[178:179], 11, v[174:175]
	v_ashrrev_i32_e32 v171, 31, v170
	v_or_b32_e32 v168, 48, v166
	v_lshl_add_u64 v[112:113], v[164:165], 0, v[178:179]
	v_lshlrev_b64 v[176:177], 11, v[170:171]
	v_ashrrev_i32_e32 v169, 31, v168
	global_load_dwordx4 v[148:151], v[112:113], off
	global_load_dwordx4 v[136:139], v[112:113], off offset:256
	v_lshl_add_u64 v[112:113], v[164:165], 0, v[176:177]
	v_lshlrev_b64 v[172:173], 11, v[168:169]
	global_load_dwordx4 v[124:127], v[112:113], off
	global_load_dwordx4 v[120:123], v[112:113], off offset:256
	v_lshl_add_u64 v[112:113], v[164:165], 0, v[172:173]
	global_load_dwordx4 v[116:119], v[112:113], off
	s_nop 0
	global_load_dwordx4 v[112:115], v[112:113], off offset:256
	v_lshl_add_u64 v[194:195], s[28:29], 0, v[194:195]
	v_lshl_add_u64 v[192:193], v[194:195], 0, v[192:193]
	s_lshl_b32 s64, s90, 2
	s_ashr_i32 s65, s64, 31
	s_waitcnt vmcnt(0)
	v_lshlrev_b32_e32 v194, 16, v184
	v_and_b32_e32 v195, 0xffff0000, v184
	v_lshlrev_b32_e32 v184, 16, v185
	v_and_b32_e32 v185, 0xffff0000, v185
	v_lshlrev_b32_e32 v196, 16, v186
	v_and_b32_e32 v197, 0xffff0000, v186
	v_lshlrev_b32_e32 v186, 16, v187
	v_and_b32_e32 v187, 0xffff0000, v187
	v_pk_add_f32 v[146:147], v[146:147], v[184:185]
	v_pk_add_f32 v[144:145], v[144:145], v[194:195]
	v_pk_add_f32 v[184:185], v[142:143], v[186:187]
	v_pk_add_f32 v[142:143], v[140:141], v[196:197]
	v_mul_f32_e32 v140, v145, v145
	v_mul_f32_e32 v141, v147, v147
	v_fmac_f32_e32 v140, v144, v144
	v_fmac_f32_e32 v141, v146, v146
	v_add_f32_e32 v140, v140, v141
	v_mul_f32_e32 v141, v143, v143
	v_fmac_f32_e32 v141, v142, v142
	v_add_f32_e32 v140, v141, v140
	v_mul_f32_e32 v141, v185, v185
	v_fmac_f32_e32 v141, v184, v184
	v_add_f32_e32 v186, v141, v140
	v_cvt_pk_bf16_f32 v140, v144, v145
	v_cvt_pk_bf16_f32 v141, v146, v147
	v_cvt_pk_bf16_f32 v142, v142, v143
	v_cvt_pk_bf16_f32 v143, v184, v185
	global_store_dwordx4 v[192:193], v[140:143], off
	v_lshlrev_b32_e32 v144, 16, v190
	v_and_b32_e32 v145, 0xffff0000, v190
	v_lshlrev_b32_e32 v140, 16, v188
	v_and_b32_e32 v141, 0xffff0000, v188
	v_lshlrev_b32_e32 v142, 16, v189
	v_and_b32_e32 v143, 0xffff0000, v189
	v_lshlrev_b32_e32 v146, 16, v191
	v_and_b32_e32 v147, 0xffff0000, v191
	v_pk_add_f32 v[134:135], v[134:135], v[142:143]
	v_pk_add_f32 v[132:133], v[132:133], v[140:141]
	v_pk_add_f32 v[140:141], v[130:131], v[146:147]
	v_pk_add_f32 v[130:131], v[128:129], v[144:145]
	v_mul_f32_e32 v128, v133, v133
	v_mul_f32_e32 v129, v135, v135
	v_fmac_f32_e32 v128, v132, v132
	v_fmac_f32_e32 v129, v134, v134
	v_add_f32_e32 v128, v128, v129
	v_mul_f32_e32 v129, v131, v131
	v_fmac_f32_e32 v129, v130, v130
	v_add_f32_e32 v128, v129, v128
	v_mul_f32_e32 v129, v141, v141
	v_fmac_f32_e32 v129, v140, v140
	v_add_f32_e32 v128, v129, v128
	v_add_f32_e32 v142, v186, v128
	v_cvt_pk_bf16_f32 v128, v132, v133
	v_cvt_pk_bf16_f32 v129, v134, v135
	v_cvt_pk_bf16_f32 v130, v130, v131
	v_cvt_pk_bf16_f32 v131, v140, v141
	global_store_dwordx4 v[192:193], v[128:131], off offset:256
	s_nop 1
	v_and_b32_e32 v129, 64, v244
	v_xor_b32_e32 v128, 16, v244
	v_add_u32_e32 v129, 64, v129
	v_cmp_lt_i32_e32 vcc, v128, v129
	v_xor_b32_e32 v131, 32, v244
	s_nop 0
	v_cndmask_b32_e32 v128, v244, v128, vcc
	v_lshlrev_b32_e32 v128, 2, v128
	s_nop 1
	v_mov_b32_e32 v130, v142
	s_nop 1
	v_permlane16_swap_b32_e32 v142, v130
	v_cmp_lt_i32_e32 vcc, v131, v129
	s_waitcnt lgkmcnt(0)
	v_add_f32_e32 v130, v142, v130
	v_cndmask_b32_e32 v129, v244, v131, vcc
	v_lshlrev_b32_e32 v129, 2, v129
	s_nop 1
	v_mov_b32_e32 v131, v130
	s_nop 1
	v_permlane32_swap_b32_e32 v130, v131
	s_and_saveexec_b64 s[38:39], s[6:7]
	s_cbranch_execz .LBB0_199
	s_waitcnt lgkmcnt(0)
	v_add_f32_e32 v132, v130, v131
	v_lshlrev_b64 v[130:131], 6, v[166:167]
	v_lshl_add_u64 v[130:131], s[30:31], 0, v[130:131]
	v_lshl_add_u64 v[130:131], s[64:65], 2, v[130:131]
	s_lshl_b32 s90, s61, 2
	v_lshl_add_u64 v[130:131], v[130:131], 0, s[90:91]
	global_store_dword v[130:131], v132, off
; __device__ __forceinline__ unsigned cvt_pk_bf16(float lo, float hi) { unsigned r; asm volatile("v_cvt_pk_bf16_f32 %0, %1, %2" : "=v"(r) : "v"(lo), "v"(hi)); return r; }
; #define GAS __attribute__((address_space(1)))
;     __device__ __forceinline__ void operator()(const f32x4 (&acc)[2][2][4][2], const Unit& u, int wr, int wc, int fr, int fq) const {
;     ...
;         for (int ai = 0; ai < 2; ++ai) {
;             u32x4 xo[4][2];
; #pragma unroll
;             for (int m = 0; m < 4; ++m)
; #pragma unroll
;                 for (int bj = 0; bj < 2; ++bj) xo[m][bj] = *(const GAS u32x4*)(xb + (size_t)(row0 + ai * 128 + m * 16) * DM + col0 + bj * 128);
;             asm volatile("" ::: "memory");
; #pragma unroll
;             for (int m = 0; m < 4; ++m) {
;                 const int row = row0 + ai * 128 + m * 16; float part = 0.f;
; #pragma unroll
;                 for (int bj = 0; bj < 2; ++bj) {
;                     bf16_t* xp = xb + (size_t)row * DM + col0 + bj * 128;
;                     const u32x4 q = xo[m][bj];
;                     f32x4 x0, x1;
;                     x0[0] = __uint_as_float(q.x << 16); x0[1] = __uint_as_float(q.x & 0xffff0000u); x0[2] = __uint_as_float(q.y << 16); x0[3] = __uint_as_float(q.y & 0xffff0000u);
;                     x1[0] = __uint_as_float(q.z << 16); x1[1] = __uint_as_float(q.z & 0xffff0000u); x1[2] = __uint_as_float(q.w << 16); x1[3] = __uint_as_float(q.w & 0xffff0000u);
;                     x0 = x0 + acc[ai][bj][m][0]; x1 = x1 + acc[ai][bj][m][1];
;                     part += (x0[0] * x0[0] + x0[1] * x0[1]) + (x0[2] * x0[2] + x0[3] * x0[3]) + (x1[0] * x1[0] + x1[1] * x1[1]) + (x1[2] * x1[2] + x1[3] * x1[3]);
;                     u32x4 w; w.x = cvt_pk_bf16(x0[0], x0[1]); w.y = cvt_pk_bf16(x0[2], x0[3]); w.z = cvt_pk_bf16(x1[0], x1[1]); w.w = cvt_pk_bf16(x1[2], x1[3]);
;                     *(GAS u32x4*)xp = w;
;                 }
;                 part += __shfl_xor(part, 16); part += __shfl_xor(part, 32);
;                 if (fq == 0) *(GAS float*)(ssacc + (size_t)row * 16 + u.pn * 4 + wc) = part;
.LBB0_199:
	s_or_b64 exec, exec, s[38:39]
	v_lshlrev_b32_e32 v132, 16, v148
	v_and_b32_e32 v133, 0xffff0000, v148
	v_lshlrev_b32_e32 v134, 16, v149
	v_and_b32_e32 v135, 0xffff0000, v149
	v_lshlrev_b32_e32 v140, 16, v150
	v_and_b32_e32 v141, 0xffff0000, v150
	v_lshlrev_b32_e32 v142, 16, v151
	v_and_b32_e32 v143, 0xffff0000, v151
	v_pk_add_f32 v[110:111], v[110:111], v[134:135]
	v_pk_add_f32 v[108:109], v[108:109], v[132:133]
	v_pk_add_f32 v[132:133], v[106:107], v[142:143]
	v_pk_add_f32 v[106:107], v[104:105], v[140:141]
	v_mul_f32_e32 v104, v109, v109
	v_mul_f32_e32 v105, v111, v111
	v_fmac_f32_e32 v104, v108, v108
	v_fmac_f32_e32 v105, v110, v110
	v_add_f32_e32 v104, v104, v105
	v_mul_f32_e32 v105, v107, v107
	v_fmac_f32_e32 v105, v106, v106
	v_add_f32_e32 v104, v105, v104
	v_mul_f32_e32 v105, v133, v133
	v_fmac_f32_e32 v105, v132, v132
	v_add_f32_e32 v140, v105, v104
	v_cvt_pk_bf16_f32 v104, v108, v109
	v_cvt_pk_bf16_f32 v105, v110, v111
	v_lshlrev_b32_e32 v108, 16, v136
	v_and_b32_e32 v109, 0xffff0000, v136
	v_lshlrev_b32_e32 v110, 16, v137
	v_and_b32_e32 v111, 0xffff0000, v137
	v_lshlrev_b32_e32 v134, 16, v138
	v_and_b32_e32 v135, 0xffff0000, v138
	v_pk_add_f32 v[102:103], v[102:103], v[110:111]
	v_pk_add_f32 v[100:101], v[100:101], v[108:109]
	v_pk_add_f32 v[110:111], v[96:97], v[134:135]
	v_mul_f32_e32 v96, v101, v101
	v_mul_f32_e32 v97, v103, v103
	v_fmac_f32_e32 v96, v100, v100
	v_fmac_f32_e32 v97, v102, v102
	v_lshlrev_b32_e32 v136, 16, v139
	v_and_b32_e32 v137, 0xffff0000, v139
	v_add_f32_e32 v96, v96, v97
	v_mul_f32_e32 v97, v111, v111
	v_pk_add_f32 v[108:109], v[98:99], v[136:137]
	v_fmac_f32_e32 v97, v110, v110
	v_add_f32_e32 v96, v97, v96
	v_mul_f32_e32 v97, v109, v109
	v_fmac_f32_e32 v97, v108, v108
	v_add_f32_e32 v96, v97, v96
	v_add_f32_e32 v96, v140, v96
	s_nop 1
	v_mov_b32_e32 v97, v96
	s_nop 1
	v_permlane16_swap_b32_e32 v96, v97
	s_waitcnt lgkmcnt(1)
	v_lshl_add_u64 v[130:131], s[28:29], 0, v[178:179]
	v_lshl_add_u64 v[130:131], v[162:163], 1, v[130:131]
	v_cvt_pk_bf16_f32 v106, v106, v107
	v_cvt_pk_bf16_f32 v107, v132, v133
	s_waitcnt lgkmcnt(0)
	v_add_f32_e32 v96, v96, v97
	s_nop 1
	v_mov_b32_e32 v97, v96
	s_nop 1
	v_permlane32_swap_b32_e32 v96, v97
	global_store_dwordx4 v[130:131], v[104:107], off
	v_cvt_pk_bf16_f32 v98, v100, v101
	v_cvt_pk_bf16_f32 v99, v102, v103
	v_cvt_pk_bf16_f32 v100, v110, v111
	v_cvt_pk_bf16_f32 v101, v108, v109
	global_store_dwordx4 v[130:131], v[98:101], off offset:256
	s_and_saveexec_b64 s[38:39], s[6:7]
	s_cbranch_execz .LBB0_201
	s_waitcnt lgkmcnt(0)
	v_add_f32_e32 v98, v96, v97
	v_lshlrev_b64 v[96:97], 6, v[174:175]
	v_lshl_add_u64 v[96:97], s[30:31], 0, v[96:97]
	v_lshl_add_u64 v[96:97], s[64:65], 2, v[96:97]
	s_lshl_b32 s90, s61, 2
	v_lshl_add_u64 v[96:97], v[96:97], 0, s[90:91]
	global_store_dword v[96:97], v98, off
.LBB0_201:
	s_or_b64 exec, exec, s[38:39]
	v_lshlrev_b32_e32 v98, 16, v124
	v_and_b32_e32 v99, 0xffff0000, v124
	v_lshlrev_b32_e32 v100, 16, v125
	v_and_b32_e32 v101, 0xffff0000, v125
	v_lshlrev_b32_e32 v102, 16, v126
	v_and_b32_e32 v103, 0xffff0000, v126
	v_lshlrev_b32_e32 v104, 16, v127
	v_and_b32_e32 v105, 0xffff0000, v127
	v_pk_add_f32 v[94:95], v[94:95], v[100:101]
	v_pk_add_f32 v[92:93], v[92:93], v[98:99]
	v_pk_add_f32 v[98:99], v[90:91], v[104:105]
	v_pk_add_f32 v[90:91], v[88:89], v[102:103]
	v_mul_f32_e32 v88, v93, v93
	v_mul_f32_e32 v89, v95, v95
	v_fmac_f32_e32 v88, v92, v92
	v_fmac_f32_e32 v89, v94, v94
	v_add_f32_e32 v88, v88, v89
	v_mul_f32_e32 v89, v91, v91
	v_fmac_f32_e32 v89, v90, v90
	v_add_f32_e32 v88, v89, v88
	v_mul_f32_e32 v89, v99, v99
	v_fmac_f32_e32 v89, v98, v98
	v_add_f32_e32 v104, v89, v88
	v_cvt_pk_bf16_f32 v88, v92, v93
	v_cvt_pk_bf16_f32 v89, v94, v95
	v_lshlrev_b32_e32 v92, 16, v120
	v_and_b32_e32 v93, 0xffff0000, v120
	v_lshlrev_b32_e32 v94, 16, v121
	v_and_b32_e32 v95, 0xffff0000, v121
	v_lshlrev_b32_e32 v100, 16, v122
	v_and_b32_e32 v101, 0xffff0000, v122
	v_pk_add_f32 v[86:87], v[86:87], v[94:95]
	v_pk_add_f32 v[84:85], v[84:85], v[92:93]
	v_pk_add_f32 v[94:95], v[80:81], v[100:101]
	v_mul_f32_e32 v80, v85, v85
	v_mul_f32_e32 v81, v87, v87
	v_fmac_f32_e32 v80, v84, v84
	v_fmac_f32_e32 v81, v86, v86
	v_lshlrev_b32_e32 v102, 16, v123
	v_and_b32_e32 v103, 0xffff0000, v123
	v_add_f32_e32 v80, v80, v81
	v_mul_f32_e32 v81, v95, v95
	v_pk_add_f32 v[92:93], v[82:83], v[102:103]
	v_fmac_f32_e32 v81, v94, v94
	v_add_f32_e32 v80, v81, v80
	v_mul_f32_e32 v81, v93, v93
	v_fmac_f32_e32 v81, v92, v92
	v_add_f32_e32 v80, v81, v80
	v_add_f32_e32 v80, v104, v80
	s_nop 1
	v_mov_b32_e32 v81, v80
	s_nop 1
	v_permlane16_swap_b32_e32 v80, v81
	s_waitcnt lgkmcnt(1)
	v_lshl_add_u64 v[96:97], s[28:29], 0, v[176:177]
	v_lshl_add_u64 v[96:97], v[162:163], 1, v[96:97]
	v_cvt_pk_bf16_f32 v90, v90, v91
	v_cvt_pk_bf16_f32 v91, v98, v99
	s_waitcnt lgkmcnt(0)
	v_add_f32_e32 v80, v80, v81
	s_nop 1
	v_mov_b32_e32 v81, v80
	s_nop 1
	v_permlane32_swap_b32_e32 v80, v81
	global_store_dwordx4 v[96:97], v[88:91], off
	v_cvt_pk_bf16_f32 v82, v84, v85
	v_cvt_pk_bf16_f32 v83, v86, v87
	v_cvt_pk_bf16_f32 v84, v94, v95
	v_cvt_pk_bf16_f32 v85, v92, v93
	global_store_dwordx4 v[96:97], v[82:85], off offset:256
	s_and_saveexec_b64 s[38:39], s[6:7]
	s_cbranch_execz .LBB0_203
	s_waitcnt lgkmcnt(0)
	v_add_f32_e32 v82, v80, v81
	v_lshlrev_b64 v[80:81], 6, v[170:171]
	v_lshl_add_u64 v[80:81], s[30:31], 0, v[80:81]
	v_lshl_add_u64 v[80:81], s[64:65], 2, v[80:81]
	s_lshl_b32 s90, s61, 2
	v_lshl_add_u64 v[80:81], v[80:81], 0, s[90:91]
	global_store_dword v[80:81], v82, off
; __device__ __forceinline__ unsigned cvt_pk_bf16(float lo, float hi) { unsigned r; asm volatile("v_cvt_pk_bf16_f32 %0, %1, %2" : "=v"(r) : "v"(lo), "v"(hi)); return r; }
; #define GAS __attribute__((address_space(1)))
;     __device__ __forceinline__ void operator()(const f32x4 (&acc)[2][2][4][2], const Unit& u, int wr, int wc, int fr, int fq) const {
;     ...
;         for (int ai = 0; ai < 2; ++ai) {
;             u32x4 xo[4][2];
; #pragma unroll
;             for (int m = 0; m < 4; ++m)
; #pragma unroll
;                 for (int bj = 0; bj < 2; ++bj) xo[m][bj] = *(const GAS u32x4*)(xb + (size_t)(row0 + ai * 128 + m * 16) * DM + col0 + bj * 128);
;             asm volatile("" ::: "memory");
; #pragma unroll
;             for (int m = 0; m < 4; ++m) {
;                 const int row = row0 + ai * 128 + m * 16; float part = 0.f;
; #pragma unroll
;                 for (int bj = 0; bj < 2; ++bj) {
;                     bf16_t* xp = xb + (size_t)row * DM + col0 + bj * 128;
;                     const u32x4 q = xo[m][bj];
;                     f32x4 x0, x1;
;                     x0[0] = __uint_as_float(q.x << 16); x0[1] = __uint_as_float(q.x & 0xffff0000u); x0[2] = __uint_as_float(q.y << 16); x0[3] = __uint_as_float(q.y & 0xffff0000u);
;                     x1[0] = __uint_as_float(q.z << 16); x1[1] = __uint_as_float(q.z & 0xffff0000u); x1[2] = __uint_as_float(q.w << 16); x1[3] = __uint_as_float(q.w & 0xffff0000u);
;                     x0 = x0 + acc[ai][bj][m][0]; x1 = x1 + acc[ai][bj][m][1];
;                     part += (x0[0] * x0[0] + x0[1] * x0[1]) + (x0[2] * x0[2] + x0[3] * x0[3]) + (x1[0] * x1[0] + x1[1] * x1[1]) + (x1[2] * x1[2] + x1[3] * x1[3]);
;                     u32x4 w; w.x = cvt_pk_bf16(x0[0], x0[1]); w.y = cvt_pk_bf16(x0[2], x0[3]); w.z = cvt_pk_bf16(x1[0], x1[1]); w.w = cvt_pk_bf16(x1[2], x1[3]);
;                     *(GAS u32x4*)xp = w;
;                 }
;                 part += __shfl_xor(part, 16); part += __shfl_xor(part, 32);
;                 if (fq == 0) *(GAS float*)(ssacc + (size_t)row * 16 + u.pn * 4 + wc) = part;
.LBB0_203:
	s_or_b64 exec, exec, s[38:39]
	v_lshlrev_b32_e32 v82, 16, v116
	v_and_b32_e32 v83, 0xffff0000, v116
	v_lshlrev_b32_e32 v84, 16, v117
	v_and_b32_e32 v85, 0xffff0000, v117
	v_lshlrev_b32_e32 v86, 16, v118
	v_and_b32_e32 v87, 0xffff0000, v118
	v_lshlrev_b32_e32 v88, 16, v119
	v_and_b32_e32 v89, 0xffff0000, v119
	v_pk_add_f32 v[78:79], v[78:79], v[84:85]
	v_pk_add_f32 v[76:77], v[76:77], v[82:83]
	v_pk_add_f32 v[82:83], v[74:75], v[88:89]
	v_pk_add_f32 v[74:75], v[72:73], v[86:87]
	v_mul_f32_e32 v72, v77, v77
	v_mul_f32_e32 v73, v79, v79
	v_fmac_f32_e32 v72, v76, v76
	v_fmac_f32_e32 v73, v78, v78
	v_add_f32_e32 v72, v72, v73
	v_mul_f32_e32 v73, v75, v75
	v_fmac_f32_e32 v73, v74, v74
	v_add_f32_e32 v72, v73, v72
	v_mul_f32_e32 v73, v83, v83
	v_fmac_f32_e32 v73, v82, v82
	v_add_f32_e32 v88, v73, v72
	v_cvt_pk_bf16_f32 v72, v76, v77
	v_cvt_pk_bf16_f32 v73, v78, v79
	v_lshlrev_b32_e32 v76, 16, v112
	v_and_b32_e32 v77, 0xffff0000, v112
	v_lshlrev_b32_e32 v78, 16, v113
	v_and_b32_e32 v79, 0xffff0000, v113
	v_lshlrev_b32_e32 v84, 16, v114
	v_and_b32_e32 v85, 0xffff0000, v114
	v_pk_add_f32 v[70:71], v[70:71], v[78:79]
	v_pk_add_f32 v[68:69], v[68:69], v[76:77]
	v_pk_add_f32 v[78:79], v[64:65], v[84:85]
	v_mul_f32_e32 v64, v69, v69
	v_mul_f32_e32 v65, v71, v71
	v_fmac_f32_e32 v64, v68, v68
	v_fmac_f32_e32 v65, v70, v70
	v_lshlrev_b32_e32 v86, 16, v115
	v_and_b32_e32 v87, 0xffff0000, v115
	v_add_f32_e32 v64, v64, v65
	v_mul_f32_e32 v65, v79, v79
	v_pk_add_f32 v[76:77], v[66:67], v[86:87]
	v_fmac_f32_e32 v65, v78, v78
	v_add_f32_e32 v64, v65, v64
	v_mul_f32_e32 v65, v77, v77
	v_fmac_f32_e32 v65, v76, v76
	v_add_f32_e32 v64, v65, v64
	v_add_f32_e32 v64, v88, v64
	s_nop 1
	v_mov_b32_e32 v65, v64
	s_nop 1
	v_permlane16_swap_b32_e32 v64, v65
	s_waitcnt lgkmcnt(1)
	v_lshl_add_u64 v[80:81], s[28:29], 0, v[172:173]
	v_lshl_add_u64 v[80:81], v[162:163], 1, v[80:81]
	v_cvt_pk_bf16_f32 v74, v74, v75
	v_cvt_pk_bf16_f32 v75, v82, v83
	s_waitcnt lgkmcnt(0)
	v_add_f32_e32 v64, v64, v65
	s_nop 1
	v_mov_b32_e32 v65, v64
	s_nop 1
	v_permlane32_swap_b32_e32 v64, v65
	global_store_dwordx4 v[80:81], v[72:75], off
	v_cvt_pk_bf16_f32 v66, v68, v69
	v_cvt_pk_bf16_f32 v67, v70, v71
	v_cvt_pk_bf16_f32 v68, v78, v79
	v_cvt_pk_bf16_f32 v69, v76, v77
	global_store_dwordx4 v[80:81], v[66:69], off offset:256
	s_and_saveexec_b64 s[38:39], s[6:7]
	s_cbranch_execz .LBB0_205
	s_waitcnt lgkmcnt(0)
	v_add_f32_e32 v66, v64, v65
	v_lshlrev_b64 v[64:65], 6, v[168:169]
	v_lshl_add_u64 v[64:65], s[30:31], 0, v[64:65]
	v_lshl_add_u64 v[64:65], s[64:65], 2, v[64:65]
	s_lshl_b32 s90, s61, 2
	v_lshl_add_u64 v[64:65], v[64:65], 0, s[90:91]
	global_store_dword v[64:65], v66, off
.LBB0_205:
	s_or_b64 exec, exec, s[38:39]
	v_add_u32_e32 v104, 0x80, v166
	v_ashrrev_i32_e32 v105, 31, v104
	v_lshlrev_b64 v[106:107], 11, v[104:105]
	s_waitcnt lgkmcnt(0)
	v_lshl_add_u64 v[64:65], v[164:165], 0, v[106:107]
	global_load_dwordx4 v[108:111], v[64:65], off
	global_load_dwordx4 v[88:91], v[64:65], off offset:256
	v_add_u32_e32 v98, 0x90, v166
	v_ashrrev_i32_e32 v99, 31, v98
	v_add_u32_e32 v94, 0xa0, v166
	v_lshlrev_b64 v[102:103], 11, v[98:99]
	v_ashrrev_i32_e32 v95, 31, v94
	v_add_u32_e32 v92, 0xb0, v166
	v_lshl_add_u64 v[64:65], v[164:165], 0, v[102:103]
	v_lshlrev_b64 v[100:101], 11, v[94:95]
	v_ashrrev_i32_e32 v93, 31, v92
	global_load_dwordx4 v[84:87], v[64:65], off
	global_load_dwordx4 v[80:83], v[64:65], off offset:256
	v_lshl_add_u64 v[64:65], v[164:165], 0, v[100:101]
	v_lshlrev_b64 v[96:97], 11, v[92:93]
	global_load_dwordx4 v[76:79], v[64:65], off
	global_load_dwordx4 v[72:75], v[64:65], off offset:256
	v_lshl_add_u64 v[64:65], v[164:165], 0, v[96:97]
	global_load_dwordx4 v[68:71], v[64:65], off
	s_nop 0
	global_load_dwordx4 v[64:67], v[64:65], off offset:256
	v_lshl_add_u64 v[106:107], s[28:29], 0, v[106:107]
	v_lshl_add_u64 v[106:107], v[162:163], 1, v[106:107]
	s_waitcnt vmcnt(7)
	v_lshlrev_b32_e32 v112, 16, v108
	v_and_b32_e32 v113, 0xffff0000, v108
	v_lshlrev_b32_e32 v108, 16, v109
	v_and_b32_e32 v109, 0xffff0000, v109
	v_lshlrev_b32_e32 v114, 16, v110
	v_and_b32_e32 v115, 0xffff0000, v110
	v_lshlrev_b32_e32 v110, 16, v111
	v_and_b32_e32 v111, 0xffff0000, v111
	v_pk_add_f32 v[62:63], v[62:63], v[108:109]
	v_pk_add_f32 v[60:61], v[60:61], v[112:113]
	v_pk_add_f32 v[108:109], v[58:59], v[110:111]
	v_pk_add_f32 v[58:59], v[56:57], v[114:115]
	v_mul_f32_e32 v56, v61, v61
	v_mul_f32_e32 v57, v63, v63
	v_fmac_f32_e32 v56, v60, v60
	v_fmac_f32_e32 v57, v62, v62
	v_add_f32_e32 v56, v56, v57
	v_mul_f32_e32 v57, v59, v59
	v_fmac_f32_e32 v57, v58, v58
	v_add_f32_e32 v56, v57, v56
	v_mul_f32_e32 v57, v109, v109
	v_fmac_f32_e32 v57, v108, v108
	v_add_f32_e32 v110, v57, v56
	v_cvt_pk_bf16_f32 v56, v60, v61
	v_cvt_pk_bf16_f32 v57, v62, v63
	v_cvt_pk_bf16_f32 v58, v58, v59
	v_cvt_pk_bf16_f32 v59, v108, v109
	global_store_dwordx4 v[106:107], v[56:59], off
	s_waitcnt vmcnt(7)
	v_lshlrev_b32_e32 v60, 16, v90
	v_and_b32_e32 v61, 0xffff0000, v90
	v_lshlrev_b32_e32 v56, 16, v88
	v_and_b32_e32 v57, 0xffff0000, v88
	v_lshlrev_b32_e32 v58, 16, v89
	v_and_b32_e32 v59, 0xffff0000, v89
	v_lshlrev_b32_e32 v62, 16, v91
	v_and_b32_e32 v63, 0xffff0000, v91
	v_pk_add_f32 v[54:55], v[54:55], v[58:59]
	v_pk_add_f32 v[52:53], v[52:53], v[56:57]
	v_pk_add_f32 v[56:57], v[50:51], v[62:63]
	v_pk_add_f32 v[50:51], v[48:49], v[60:61]
	v_mul_f32_e32 v48, v53, v53
	v_mul_f32_e32 v49, v55, v55
	v_fmac_f32_e32 v48, v52, v52
	v_fmac_f32_e32 v49, v54, v54
	v_add_f32_e32 v48, v48, v49
	v_mul_f32_e32 v49, v51, v51
	v_fmac_f32_e32 v49, v50, v50
	v_add_f32_e32 v48, v49, v48
	v_mul_f32_e32 v49, v57, v57
	v_fmac_f32_e32 v49, v56, v56
	v_add_f32_e32 v48, v49, v48
	v_add_f32_e32 v58, v110, v48
	v_cvt_pk_bf16_f32 v48, v52, v53
	v_cvt_pk_bf16_f32 v49, v54, v55
	v_cvt_pk_bf16_f32 v50, v50, v51
	v_cvt_pk_bf16_f32 v51, v56, v57
	global_store_dwordx4 v[106:107], v[48:51], off offset:256
	s_nop 1
	v_mov_b32_e32 v48, v58
	s_nop 1
	v_permlane16_swap_b32_e32 v58, v48
	s_waitcnt lgkmcnt(0)
	v_add_f32_e32 v48, v58, v48
	s_nop 1
	v_mov_b32_e32 v49, v48
	s_nop 1
	v_permlane32_swap_b32_e32 v48, v49
	s_and_saveexec_b64 s[38:39], s[6:7]
	s_cbranch_execz .LBB0_207
	s_waitcnt lgkmcnt(0)
	v_add_f32_e32 v50, v48, v49
	v_lshlrev_b64 v[48:49], 6, v[104:105]
	v_lshl_add_u64 v[48:49], s[30:31], 0, v[48:49]
	v_lshl_add_u64 v[48:49], s[64:65], 2, v[48:49]
	s_lshl_b32 s90, s61, 2
	v_lshl_add_u64 v[48:49], v[48:49], 0, s[90:91]
	global_store_dword v[48:49], v50, off
; __device__ __forceinline__ unsigned cvt_pk_bf16(float lo, float hi) { unsigned r; asm volatile("v_cvt_pk_bf16_f32 %0, %1, %2" : "=v"(r) : "v"(lo), "v"(hi)); return r; }
; #define GAS __attribute__((address_space(1)))
;     __device__ __forceinline__ void operator()(const f32x4 (&acc)[2][2][4][2], const Unit& u, int wr, int wc, int fr, int fq) const {
;     ...
;         for (int ai = 0; ai < 2; ++ai) {
;             u32x4 xo[4][2];
; #pragma unroll
;             for (int m = 0; m < 4; ++m)
; #pragma unroll
;                 for (int bj = 0; bj < 2; ++bj) xo[m][bj] = *(const GAS u32x4*)(xb + (size_t)(row0 + ai * 128 + m * 16) * DM + col0 + bj * 128);
;             asm volatile("" ::: "memory");
; #pragma unroll
;             for (int m = 0; m < 4; ++m) {
;                 const int row = row0 + ai * 128 + m * 16; float part = 0.f;
; #pragma unroll
;                 for (int bj = 0; bj < 2; ++bj) {
;                     bf16_t* xp = xb + (size_t)row * DM + col0 + bj * 128;
;                     const u32x4 q = xo[m][bj];
;                     f32x4 x0, x1;
;                     x0[0] = __uint_as_float(q.x << 16); x0[1] = __uint_as_float(q.x & 0xffff0000u); x0[2] = __uint_as_float(q.y << 16); x0[3] = __uint_as_float(q.y & 0xffff0000u);
;                     x1[0] = __uint_as_float(q.z << 16); x1[1] = __uint_as_float(q.z & 0xffff0000u); x1[2] = __uint_as_float(q.w << 16); x1[3] = __uint_as_float(q.w & 0xffff0000u);
;                     x0 = x0 + acc[ai][bj][m][0]; x1 = x1 + acc[ai][bj][m][1];
;                     part += (x0[0] * x0[0] + x0[1] * x0[1]) + (x0[2] * x0[2] + x0[3] * x0[3]) + (x1[0] * x1[0] + x1[1] * x1[1]) + (x1[2] * x1[2] + x1[3] * x1[3]);
;                     u32x4 w; w.x = cvt_pk_bf16(x0[0], x0[1]); w.y = cvt_pk_bf16(x0[2], x0[3]); w.z = cvt_pk_bf16(x1[0], x1[1]); w.w = cvt_pk_bf16(x1[2], x1[3]);
;                     *(GAS u32x4*)xp = w;
;                 }
;                 part += __shfl_xor(part, 16); part += __shfl_xor(part, 32);
;                 if (fq == 0) *(GAS float*)(ssacc + (size_t)row * 16 + u.pn * 4 + wc) = part;
.LBB0_207:
	s_or_b64 exec, exec, s[38:39]
	s_waitcnt vmcnt(7)
	v_lshlrev_b32_e32 v50, 16, v84
	v_and_b32_e32 v51, 0xffff0000, v84
	v_lshlrev_b32_e32 v52, 16, v85
	v_and_b32_e32 v53, 0xffff0000, v85
	v_lshlrev_b32_e32 v54, 16, v86
	v_and_b32_e32 v55, 0xffff0000, v86
	v_lshlrev_b32_e32 v56, 16, v87
	v_and_b32_e32 v57, 0xffff0000, v87
	v_pk_add_f32 v[46:47], v[46:47], v[52:53]
	v_pk_add_f32 v[44:45], v[44:45], v[50:51]
	v_pk_add_f32 v[50:51], v[42:43], v[56:57]
	v_pk_add_f32 v[42:43], v[40:41], v[54:55]
	v_mul_f32_e32 v40, v45, v45
	v_mul_f32_e32 v41, v47, v47
	v_fmac_f32_e32 v40, v44, v44
	v_fmac_f32_e32 v41, v46, v46
	v_add_f32_e32 v40, v40, v41
	v_mul_f32_e32 v41, v43, v43
	v_fmac_f32_e32 v41, v42, v42
	v_add_f32_e32 v40, v41, v40
	v_mul_f32_e32 v41, v51, v51
	v_fmac_f32_e32 v41, v50, v50
	v_add_f32_e32 v56, v41, v40
	v_cvt_pk_bf16_f32 v40, v44, v45
	v_cvt_pk_bf16_f32 v41, v46, v47
	s_waitcnt vmcnt(6)
	v_lshlrev_b32_e32 v44, 16, v80
	v_and_b32_e32 v45, 0xffff0000, v80
	v_lshlrev_b32_e32 v46, 16, v81
	v_and_b32_e32 v47, 0xffff0000, v81
	v_lshlrev_b32_e32 v52, 16, v82
	v_and_b32_e32 v53, 0xffff0000, v82
	v_pk_add_f32 v[38:39], v[38:39], v[46:47]
	v_pk_add_f32 v[36:37], v[36:37], v[44:45]
	v_pk_add_f32 v[46:47], v[32:33], v[52:53]
	v_mul_f32_e32 v32, v37, v37
	v_mul_f32_e32 v33, v39, v39
	v_fmac_f32_e32 v32, v36, v36
	v_fmac_f32_e32 v33, v38, v38
	v_lshlrev_b32_e32 v54, 16, v83
	v_and_b32_e32 v55, 0xffff0000, v83
	v_add_f32_e32 v32, v32, v33
	v_mul_f32_e32 v33, v47, v47
	v_pk_add_f32 v[44:45], v[34:35], v[54:55]
	v_fmac_f32_e32 v33, v46, v46
	v_add_f32_e32 v32, v33, v32
	v_mul_f32_e32 v33, v45, v45
	v_fmac_f32_e32 v33, v44, v44
	v_add_f32_e32 v32, v33, v32
	v_add_f32_e32 v32, v56, v32
	s_nop 1
	v_mov_b32_e32 v33, v32
	s_nop 1
	v_permlane16_swap_b32_e32 v32, v33
	s_waitcnt lgkmcnt(1)
	v_lshl_add_u64 v[48:49], s[28:29], 0, v[102:103]
	v_lshl_add_u64 v[48:49], v[162:163], 1, v[48:49]
	v_cvt_pk_bf16_f32 v42, v42, v43
	v_cvt_pk_bf16_f32 v43, v50, v51
	s_waitcnt lgkmcnt(0)
	v_add_f32_e32 v32, v32, v33
	s_nop 1
	v_mov_b32_e32 v33, v32
	s_nop 1
	v_permlane32_swap_b32_e32 v32, v33
	global_store_dwordx4 v[48:49], v[40:43], off
	v_cvt_pk_bf16_f32 v34, v36, v37
	v_cvt_pk_bf16_f32 v35, v38, v39
	v_cvt_pk_bf16_f32 v36, v46, v47
	v_cvt_pk_bf16_f32 v37, v44, v45
	global_store_dwordx4 v[48:49], v[34:37], off offset:256
	s_and_saveexec_b64 s[38:39], s[6:7]
	s_cbranch_execz .LBB0_209
	s_waitcnt lgkmcnt(0)
	v_add_f32_e32 v34, v32, v33
	v_lshlrev_b64 v[32:33], 6, v[98:99]
	v_lshl_add_u64 v[32:33], s[30:31], 0, v[32:33]
	v_lshl_add_u64 v[32:33], s[64:65], 2, v[32:33]
	s_lshl_b32 s90, s61, 2
	v_lshl_add_u64 v[32:33], v[32:33], 0, s[90:91]
	global_store_dword v[32:33], v34, off
; __device__ __forceinline__ unsigned cvt_pk_bf16(float lo, float hi) { unsigned r; asm volatile("v_cvt_pk_bf16_f32 %0, %1, %2" : "=v"(r) : "v"(lo), "v"(hi)); return r; }
; #define GAS __attribute__((address_space(1)))
;     __device__ __forceinline__ void operator()(const f32x4 (&acc)[2][2][4][2], const Unit& u, int wr, int wc, int fr, int fq) const {
;     ...
;         for (int ai = 0; ai < 2; ++ai) {
;             u32x4 xo[4][2];
; #pragma unroll
;             for (int m = 0; m < 4; ++m)
; #pragma unroll
;                 for (int bj = 0; bj < 2; ++bj) xo[m][bj] = *(const GAS u32x4*)(xb + (size_t)(row0 + ai * 128 + m * 16) * DM + col0 + bj * 128);
;             asm volatile("" ::: "memory");
; #pragma unroll
;             for (int m = 0; m < 4; ++m) {
;                 const int row = row0 + ai * 128 + m * 16; float part = 0.f;
; #pragma unroll
;                 for (int bj = 0; bj < 2; ++bj) {
;                     bf16_t* xp = xb + (size_t)row * DM + col0 + bj * 128;
;                     const u32x4 q = xo[m][bj];
;                     f32x4 x0, x1;
;                     x0[0] = __uint_as_float(q.x << 16); x0[1] = __uint_as_float(q.x & 0xffff0000u); x0[2] = __uint_as_float(q.y << 16); x0[3] = __uint_as_float(q.y & 0xffff0000u);
;                     x1[0] = __uint_as_float(q.z << 16); x1[1] = __uint_as_float(q.z & 0xffff0000u); x1[2] = __uint_as_float(q.w << 16); x1[3] = __uint_as_float(q.w & 0xffff0000u);
;                     x0 = x0 + acc[ai][bj][m][0]; x1 = x1 + acc[ai][bj][m][1];
;                     part += (x0[0] * x0[0] + x0[1] * x0[1]) + (x0[2] * x0[2] + x0[3] * x0[3]) + (x1[0] * x1[0] + x1[1] * x1[1]) + (x1[2] * x1[2] + x1[3] * x1[3]);
;                     u32x4 w; w.x = cvt_pk_bf16(x0[0], x0[1]); w.y = cvt_pk_bf16(x0[2], x0[3]); w.z = cvt_pk_bf16(x1[0], x1[1]); w.w = cvt_pk_bf16(x1[2], x1[3]);
;                     *(GAS u32x4*)xp = w;
;                 }
;                 part += __shfl_xor(part, 16); part += __shfl_xor(part, 32);
;                 if (fq == 0) *(GAS float*)(ssacc + (size_t)row * 16 + u.pn * 4 + wc) = part;
.LBB0_209:
	s_or_b64 exec, exec, s[38:39]
	s_waitcnt vmcnt(7)
	v_lshlrev_b32_e32 v34, 16, v76
	v_and_b32_e32 v35, 0xffff0000, v76
	v_lshlrev_b32_e32 v36, 16, v77
	v_and_b32_e32 v37, 0xffff0000, v77
	v_lshlrev_b32_e32 v38, 16, v78
	v_and_b32_e32 v39, 0xffff0000, v78
	v_lshlrev_b32_e32 v40, 16, v79
	v_and_b32_e32 v41, 0xffff0000, v79
	v_pk_add_f32 v[30:31], v[30:31], v[36:37]
	v_pk_add_f32 v[28:29], v[28:29], v[34:35]
	v_pk_add_f32 v[34:35], v[26:27], v[40:41]
	v_pk_add_f32 v[26:27], v[24:25], v[38:39]
	v_mul_f32_e32 v24, v29, v29
	v_mul_f32_e32 v25, v31, v31
	v_fmac_f32_e32 v24, v28, v28
	v_fmac_f32_e32 v25, v30, v30
	v_add_f32_e32 v24, v24, v25
	v_mul_f32_e32 v25, v27, v27
	v_fmac_f32_e32 v25, v26, v26
	v_add_f32_e32 v24, v25, v24
	v_mul_f32_e32 v25, v35, v35
	v_fmac_f32_e32 v25, v34, v34
	v_add_f32_e32 v40, v25, v24
	v_cvt_pk_bf16_f32 v24, v28, v29
	v_cvt_pk_bf16_f32 v25, v30, v31
	s_waitcnt vmcnt(6)
	v_lshlrev_b32_e32 v28, 16, v72
	v_and_b32_e32 v29, 0xffff0000, v72
	v_lshlrev_b32_e32 v30, 16, v73
	v_and_b32_e32 v31, 0xffff0000, v73
	v_lshlrev_b32_e32 v36, 16, v74
	v_and_b32_e32 v37, 0xffff0000, v74
	v_pk_add_f32 v[22:23], v[22:23], v[30:31]
	v_pk_add_f32 v[20:21], v[20:21], v[28:29]
	v_pk_add_f32 v[30:31], v[16:17], v[36:37]
	v_mul_f32_e32 v16, v21, v21
	v_mul_f32_e32 v17, v23, v23
	v_fmac_f32_e32 v16, v20, v20
	v_fmac_f32_e32 v17, v22, v22
	v_lshlrev_b32_e32 v38, 16, v75
	v_and_b32_e32 v39, 0xffff0000, v75
	v_add_f32_e32 v16, v16, v17
	v_mul_f32_e32 v17, v31, v31
	v_pk_add_f32 v[28:29], v[18:19], v[38:39]
	v_fmac_f32_e32 v17, v30, v30
	v_add_f32_e32 v16, v17, v16
	v_mul_f32_e32 v17, v29, v29
	v_fmac_f32_e32 v17, v28, v28
	v_add_f32_e32 v16, v17, v16
	v_add_f32_e32 v16, v40, v16
	s_nop 1
	v_mov_b32_e32 v17, v16
	s_nop 1
	v_permlane16_swap_b32_e32 v16, v17
	s_waitcnt lgkmcnt(1)
	v_lshl_add_u64 v[32:33], s[28:29], 0, v[100:101]
	v_lshl_add_u64 v[32:33], v[162:163], 1, v[32:33]
	v_cvt_pk_bf16_f32 v26, v26, v27
	v_cvt_pk_bf16_f32 v27, v34, v35
	s_waitcnt lgkmcnt(0)
	v_add_f32_e32 v16, v16, v17
	s_nop 1
	v_mov_b32_e32 v17, v16
	s_nop 1
	v_permlane32_swap_b32_e32 v16, v17
	global_store_dwordx4 v[32:33], v[24:27], off
	v_cvt_pk_bf16_f32 v18, v20, v21
	v_cvt_pk_bf16_f32 v19, v22, v23
	v_cvt_pk_bf16_f32 v20, v30, v31
	v_cvt_pk_bf16_f32 v21, v28, v29
	global_store_dwordx4 v[32:33], v[18:21], off offset:256
	s_and_saveexec_b64 s[38:39], s[6:7]
	s_cbranch_execz .LBB0_211
	s_waitcnt lgkmcnt(0)
	v_add_f32_e32 v18, v16, v17
	v_lshlrev_b64 v[16:17], 6, v[94:95]
	v_lshl_add_u64 v[16:17], s[30:31], 0, v[16:17]
	v_lshl_add_u64 v[16:17], s[64:65], 2, v[16:17]
	s_lshl_b32 s90, s61, 2
	v_lshl_add_u64 v[16:17], v[16:17], 0, s[90:91]
	global_store_dword v[16:17], v18, off
.LBB0_211:
	s_or_b64 exec, exec, s[38:39]
	s_waitcnt vmcnt(7)
	v_lshlrev_b32_e32 v18, 16, v68
	v_and_b32_e32 v19, 0xffff0000, v68
	v_lshlrev_b32_e32 v20, 16, v69
	v_and_b32_e32 v21, 0xffff0000, v69
	v_lshlrev_b32_e32 v22, 16, v70
	v_and_b32_e32 v23, 0xffff0000, v70
	v_lshlrev_b32_e32 v24, 16, v71
	v_and_b32_e32 v25, 0xffff0000, v71
	v_pk_add_f32 v[14:15], v[14:15], v[20:21]
	v_pk_add_f32 v[12:13], v[12:13], v[18:19]
	v_pk_add_f32 v[18:19], v[10:11], v[24:25]
	v_pk_add_f32 v[10:11], v[8:9], v[22:23]
	v_mul_f32_e32 v8, v13, v13
	v_mul_f32_e32 v9, v15, v15
	v_fmac_f32_e32 v8, v12, v12
	v_fmac_f32_e32 v9, v14, v14
	v_add_f32_e32 v8, v8, v9
	v_mul_f32_e32 v9, v11, v11
	v_fmac_f32_e32 v9, v10, v10
	v_add_f32_e32 v8, v9, v8
	v_mul_f32_e32 v9, v19, v19
	v_fmac_f32_e32 v9, v18, v18
	v_add_f32_e32 v24, v9, v8
	v_cvt_pk_bf16_f32 v8, v12, v13
	v_cvt_pk_bf16_f32 v9, v14, v15
	s_waitcnt vmcnt(6)
	v_lshlrev_b32_e32 v12, 16, v64
	v_and_b32_e32 v13, 0xffff0000, v64
	v_lshlrev_b32_e32 v14, 16, v65
	v_and_b32_e32 v15, 0xffff0000, v65
	v_lshlrev_b32_e32 v20, 16, v66
	v_and_b32_e32 v21, 0xffff0000, v66
	v_pk_add_f32 v[6:7], v[6:7], v[14:15]
	v_pk_add_f32 v[4:5], v[4:5], v[12:13]
	v_pk_add_f32 v[14:15], v[0:1], v[20:21]
	v_mul_f32_e32 v0, v5, v5
	v_mul_f32_e32 v1, v7, v7
	v_fmac_f32_e32 v0, v4, v4
	v_fmac_f32_e32 v1, v6, v6
	v_lshlrev_b32_e32 v22, 16, v67
	v_and_b32_e32 v23, 0xffff0000, v67
	v_add_f32_e32 v0, v0, v1
	v_mul_f32_e32 v1, v15, v15
	v_pk_add_f32 v[12:13], v[2:3], v[22:23]
	v_fmac_f32_e32 v1, v14, v14
	v_add_f32_e32 v0, v1, v0
	v_mul_f32_e32 v1, v13, v13
	v_fmac_f32_e32 v1, v12, v12
	v_add_f32_e32 v0, v1, v0
	v_add_f32_e32 v0, v24, v0
	s_nop 1
	v_mov_b32_e32 v1, v0
	s_nop 1
	v_permlane16_swap_b32_e32 v0, v1
	s_waitcnt lgkmcnt(1)
	v_lshl_add_u64 v[16:17], s[28:29], 0, v[96:97]
	v_lshl_add_u64 v[16:17], v[162:163], 1, v[16:17]
	v_cvt_pk_bf16_f32 v10, v10, v11
	v_cvt_pk_bf16_f32 v11, v18, v19
	s_waitcnt lgkmcnt(0)
	v_add_f32_e32 v0, v0, v1
	s_nop 1
	v_mov_b32_e32 v1, v0
	s_nop 1
	v_permlane32_swap_b32_e32 v0, v1
	global_store_dwordx4 v[16:17], v[8:11], off
	v_cvt_pk_bf16_f32 v2, v4, v5
	v_cvt_pk_bf16_f32 v3, v6, v7
	v_cvt_pk_bf16_f32 v4, v14, v15
	v_cvt_pk_bf16_f32 v5, v12, v13
	global_store_dwordx4 v[16:17], v[2:5], off offset:256
	s_and_saveexec_b64 s[38:39], s[6:7]
	s_cbranch_execz .LBB0_213
	s_waitcnt lgkmcnt(0)
	v_add_f32_e32 v2, v0, v1
	v_lshlrev_b64 v[0:1], 6, v[92:93]
	v_lshl_add_u64 v[0:1], s[30:31], 0, v[0:1]
	v_lshl_add_u64 v[0:1], s[64:65], 2, v[0:1]
	s_lshl_b32 s90, s61, 2
	v_lshl_add_u64 v[0:1], v[0:1], 0, s[90:91]
	global_store_dword v[0:1], v2, off

; __device__ __forceinline__ unsigned cvt_pk_bf16(float lo, float hi) { unsigned r; asm volatile("v_cvt_pk_bf16_f32 %0, %1, %2" : "=v"(r) : "v"(lo), "v"(hi)); return r; }
; #define GAS __attribute__((address_space(1)))
;     __device__ __forceinline__ void operator()(const f32x4 (&acc)[2][2][4][2], const Unit& u, int wr, int wc, int fr, int fq) const {
;         const int row0 = u.pm * 256 + wr * 64 + fr; const int col0 = u.pn * 256 + wc * 32 + 8 * fq;
; #pragma unroll
;         for (int ai = 0; ai < 2; ++ai) {
;             u32x4 xo[4][2];
; #pragma unroll
;             for (int m = 0; m < 4; ++m)
; #pragma unroll
;                 for (int bj = 0; bj < 2; ++bj) xo[m][bj] = *(const GAS u32x4*)(xb + (size_t)(row0 + ai * 128 + m * 16) * DM + col0 + bj * 128);
;             asm volatile("" ::: "memory");
; #pragma unroll
;             for (int m = 0; m < 4; ++m) {
;                 const int row = row0 + ai * 128 + m * 16; float part = 0.f;
; #pragma unroll
;                 for (int bj = 0; bj < 2; ++bj) {
;                     bf16_t* xp = xb + (size_t)row * DM + col0 + bj * 128;
;                     const u32x4 q = xo[m][bj];
;                     f32x4 x0, x1;
;                     x0[0] = __uint_as_float(q.x << 16); x0[1] = __uint_as_float(q.x & 0xffff0000u); x0[2] = __uint_as_float(q.y << 16); x0[3] = __uint_as_float(q.y & 0xffff0000u);
;                     x1[0] = __uint_as_float(q.z << 16); x1[1] = __uint_as_float(q.z & 0xffff0000u); x1[2] = __uint_as_float(q.w << 16); x1[3] = __uint_as_float(q.w & 0xffff0000u);
;                     x0 = x0 + acc[ai][bj][m][0]; x1 = x1 + acc[ai][bj][m][1];
;                     part += (x0[0] * x0[0] + x0[1] * x0[1]) + (x0[2] * x0[2] + x0[3] * x0[3]) + (x1[0] * x1[0] + x1[1] * x1[1]) + (x1[2] * x1[2] + x1[3] * x1[3]);
;                     u32x4 w; w.x = cvt_pk_bf16(x0[0], x0[1]); w.y = cvt_pk_bf16(x0[2], x0[3]); w.z = cvt_pk_bf16(x1[0], x1[1]); w.w = cvt_pk_bf16(x1[2], x1[3]);
;                     *(GAS u32x4*)xp = w;
;                 }
;                 part += __shfl_xor(part, 16); part += __shfl_xor(part, 32);
;                 if (fq == 0) *(GAS float*)(ssacc + (size_t)row * 16 + u.pn * 4 + wc) = part;
.LBB0_297:
	v_lshl_or_b32 v162, s87, 8, v182
	v_lshl_add_u32 v166, s40, 8, v180
	v_ashrrev_i32_e32 v163, 31, v162
	v_lshlrev_b64 v[192:193], 1, v[162:163]
	v_ashrrev_i32_e32 v167, 31, v166
	v_lshl_add_u64 v[164:165], s[24:25], 0, v[192:193]
	v_lshlrev_b64 v[194:195], 11, v[166:167]
	v_lshl_add_u64 v[112:113], v[164:165], 0, v[194:195]
	global_load_dwordx4 v[184:187], v[112:113], off
	global_load_dwordx4 v[188:191], v[112:113], off offset:256
	v_or_b32_e32 v174, 16, v166
	v_ashrrev_i32_e32 v175, 31, v174
	v_or_b32_e32 v170, 32, v166
	v_lshlrev_b64 v[178:179], 11, v[174:175]
	v_ashrrev_i32_e32 v171, 31, v170
	v_or_b32_e32 v168, 48, v166
	v_lshl_add_u64 v[112:113], v[164:165], 0, v[178:179]
	v_lshlrev_b64 v[176:177], 11, v[170:171]
	v_ashrrev_i32_e32 v169, 31, v168
	global_load_dwordx4 v[148:151], v[112:113], off
	global_load_dwordx4 v[136:139], v[112:113], off offset:256
	v_lshl_add_u64 v[112:113], v[164:165], 0, v[176:177]
	v_lshlrev_b64 v[172:173], 11, v[168:169]
	global_load_dwordx4 v[124:127], v[112:113], off
	global_load_dwordx4 v[120:123], v[112:113], off offset:256
	v_lshl_add_u64 v[112:113], v[164:165], 0, v[172:173]
	global_load_dwordx4 v[116:119], v[112:113], off
	s_nop 0
	global_load_dwordx4 v[112:115], v[112:113], off offset:256
	v_lshl_add_u64 v[194:195], s[24:25], 0, v[194:195]
	v_lshl_add_u64 v[192:193], v[194:195], 0, v[192:193]
	s_lshl_b32 s34, s87, 2
	s_ashr_i32 s35, s34, 31
	s_waitcnt vmcnt(0)
	v_lshlrev_b32_e32 v194, 16, v184
	v_and_b32_e32 v195, 0xffff0000, v184
	v_lshlrev_b32_e32 v184, 16, v185
	v_and_b32_e32 v185, 0xffff0000, v185
	v_lshlrev_b32_e32 v196, 16, v186
	v_and_b32_e32 v197, 0xffff0000, v186
	v_lshlrev_b32_e32 v186, 16, v187
	v_and_b32_e32 v187, 0xffff0000, v187
	v_pk_add_f32 v[146:147], v[146:147], v[184:185]
	v_pk_add_f32 v[144:145], v[144:145], v[194:195]
	v_pk_add_f32 v[184:185], v[142:143], v[186:187]
	v_pk_add_f32 v[142:143], v[140:141], v[196:197]
	v_mul_f32_e32 v140, v145, v145
	v_mul_f32_e32 v141, v147, v147
	v_fmac_f32_e32 v140, v144, v144
	v_fmac_f32_e32 v141, v146, v146
	v_add_f32_e32 v140, v140, v141
	v_mul_f32_e32 v141, v143, v143
	v_fmac_f32_e32 v141, v142, v142
	v_add_f32_e32 v140, v141, v140
	v_mul_f32_e32 v141, v185, v185
	v_fmac_f32_e32 v141, v184, v184
	v_add_f32_e32 v186, v141, v140
	v_cvt_pk_bf16_f32 v140, v144, v145
	v_cvt_pk_bf16_f32 v141, v146, v147
	v_cvt_pk_bf16_f32 v142, v142, v143
	v_cvt_pk_bf16_f32 v143, v184, v185
	global_store_dwordx4 v[192:193], v[140:143], off
	v_lshlrev_b32_e32 v144, 16, v190
	v_and_b32_e32 v145, 0xffff0000, v190
	v_lshlrev_b32_e32 v140, 16, v188
	v_and_b32_e32 v141, 0xffff0000, v188
	v_lshlrev_b32_e32 v142, 16, v189
	v_and_b32_e32 v143, 0xffff0000, v189
	v_lshlrev_b32_e32 v146, 16, v191
	v_and_b32_e32 v147, 0xffff0000, v191
	v_pk_add_f32 v[134:135], v[134:135], v[142:143]
	v_pk_add_f32 v[132:133], v[132:133], v[140:141]
	v_pk_add_f32 v[140:141], v[130:131], v[146:147]
	v_pk_add_f32 v[130:131], v[128:129], v[144:145]
	v_mul_f32_e32 v128, v133, v133
	v_mul_f32_e32 v129, v135, v135
	v_fmac_f32_e32 v128, v132, v132
	v_fmac_f32_e32 v129, v134, v134
	v_add_f32_e32 v128, v128, v129
	v_mul_f32_e32 v129, v131, v131
	v_fmac_f32_e32 v129, v130, v130
	v_add_f32_e32 v128, v129, v128
	v_mul_f32_e32 v129, v141, v141
	v_fmac_f32_e32 v129, v140, v140
	v_add_f32_e32 v128, v129, v128
	v_add_f32_e32 v142, v186, v128
	v_cvt_pk_bf16_f32 v128, v132, v133
	v_cvt_pk_bf16_f32 v129, v134, v135
	v_cvt_pk_bf16_f32 v130, v130, v131
	v_cvt_pk_bf16_f32 v131, v140, v141
	global_store_dwordx4 v[192:193], v[128:131], off offset:256
	s_nop 1
	v_and_b32_e32 v129, 64, v244
	v_xor_b32_e32 v128, 16, v244
	v_add_u32_e32 v129, 64, v129
	v_cmp_lt_i32_e32 vcc, v128, v129
	v_xor_b32_e32 v131, 32, v244
	s_nop 0
	v_cndmask_b32_e32 v128, v244, v128, vcc
	v_lshlrev_b32_e32 v128, 2, v128
	s_nop 1
	v_mov_b32_e32 v130, v142
	s_nop 1
	v_permlane16_swap_b32_e32 v142, v130
	v_cmp_lt_i32_e32 vcc, v131, v129
	s_waitcnt lgkmcnt(0)
	v_add_f32_e32 v130, v142, v130
	v_cndmask_b32_e32 v129, v244, v131, vcc
	v_lshlrev_b32_e32 v129, 2, v129
	s_nop 1
	v_mov_b32_e32 v131, v130
	s_nop 1
	v_permlane32_swap_b32_e32 v130, v131
	s_and_saveexec_b64 s[36:37], s[6:7]
	s_cbranch_execz .LBB0_299
	s_waitcnt lgkmcnt(0)
	v_add_f32_e32 v132, v130, v131
	v_lshlrev_b64 v[130:131], 6, v[166:167]
	v_lshl_add_u64 v[130:131], s[26:27], 0, v[130:131]
	v_lshl_add_u64 v[130:131], s[34:35], 2, v[130:131]
	s_lshl_b32 s90, s61, 2
	v_lshl_add_u64 v[130:131], v[130:131], 0, s[90:91]
	global_store_dword v[130:131], v132, off
; __device__ __forceinline__ unsigned cvt_pk_bf16(float lo, float hi) { unsigned r; asm volatile("v_cvt_pk_bf16_f32 %0, %1, %2" : "=v"(r) : "v"(lo), "v"(hi)); return r; }
; #define GAS __attribute__((address_space(1)))
;     __device__ __forceinline__ void operator()(const f32x4 (&acc)[2][2][4][2], const Unit& u, int wr, int wc, int fr, int fq) const {
;     ...
;         for (int ai = 0; ai < 2; ++ai) {
;             u32x4 xo[4][2];
; #pragma unroll
;             for (int m = 0; m < 4; ++m)
; #pragma unroll
;                 for (int bj = 0; bj < 2; ++bj) xo[m][bj] = *(const GAS u32x4*)(xb + (size_t)(row0 + ai * 128 + m * 16) * DM + col0 + bj * 128);
;             asm volatile("" ::: "memory");
; #pragma unroll
;             for (int m = 0; m < 4; ++m) {
;                 const int row = row0 + ai * 128 + m * 16; float part = 0.f;
; #pragma unroll
;                 for (int bj = 0; bj < 2; ++bj) {
;                     bf16_t* xp = xb + (size_t)row * DM + col0 + bj * 128;
;                     const u32x4 q = xo[m][bj];
;                     f32x4 x0, x1;
;                     x0[0] = __uint_as_float(q.x << 16); x0[1] = __uint_as_float(q.x & 0xffff0000u); x0[2] = __uint_as_float(q.y << 16); x0[3] = __uint_as_float(q.y & 0xffff0000u);
;                     x1[0] = __uint_as_float(q.z << 16); x1[1] = __uint_as_float(q.z & 0xffff0000u); x1[2] = __uint_as_float(q.w << 16); x1[3] = __uint_as_float(q.w & 0xffff0000u);
;                     x0 = x0 + acc[ai][bj][m][0]; x1 = x1 + acc[ai][bj][m][1];
;                     part += (x0[0] * x0[0] + x0[1] * x0[1]) + (x0[2] * x0[2] + x0[3] * x0[3]) + (x1[0] * x1[0] + x1[1] * x1[1]) + (x1[2] * x1[2] + x1[3] * x1[3]);
;                     u32x4 w; w.x = cvt_pk_bf16(x0[0], x0[1]); w.y = cvt_pk_bf16(x0[2], x0[3]); w.z = cvt_pk_bf16(x1[0], x1[1]); w.w = cvt_pk_bf16(x1[2], x1[3]);
;                     *(GAS u32x4*)xp = w;
;                 }
;                 part += __shfl_xor(part, 16); part += __shfl_xor(part, 32);
;                 if (fq == 0) *(GAS float*)(ssacc + (size_t)row * 16 + u.pn * 4 + wc) = part;
.LBB0_299:
	s_or_b64 exec, exec, s[36:37]
	v_lshlrev_b32_e32 v132, 16, v148
	v_and_b32_e32 v133, 0xffff0000, v148
	v_lshlrev_b32_e32 v134, 16, v149
	v_and_b32_e32 v135, 0xffff0000, v149
	v_lshlrev_b32_e32 v140, 16, v150
	v_and_b32_e32 v141, 0xffff0000, v150
	v_lshlrev_b32_e32 v142, 16, v151
	v_and_b32_e32 v143, 0xffff0000, v151
	v_pk_add_f32 v[110:111], v[110:111], v[134:135]
	v_pk_add_f32 v[108:109], v[108:109], v[132:133]
	v_pk_add_f32 v[132:133], v[106:107], v[142:143]
	v_pk_add_f32 v[106:107], v[104:105], v[140:141]
	v_mul_f32_e32 v104, v109, v109
	v_mul_f32_e32 v105, v111, v111
	v_fmac_f32_e32 v104, v108, v108
	v_fmac_f32_e32 v105, v110, v110
	v_add_f32_e32 v104, v104, v105
	v_mul_f32_e32 v105, v107, v107
	v_fmac_f32_e32 v105, v106, v106
	v_add_f32_e32 v104, v105, v104
	v_mul_f32_e32 v105, v133, v133
	v_fmac_f32_e32 v105, v132, v132
	v_add_f32_e32 v140, v105, v104
	v_cvt_pk_bf16_f32 v104, v108, v109
	v_cvt_pk_bf16_f32 v105, v110, v111
	v_lshlrev_b32_e32 v108, 16, v136
	v_and_b32_e32 v109, 0xffff0000, v136
	v_lshlrev_b32_e32 v110, 16, v137
	v_and_b32_e32 v111, 0xffff0000, v137
	v_lshlrev_b32_e32 v134, 16, v138
	v_and_b32_e32 v135, 0xffff0000, v138
	v_pk_add_f32 v[102:103], v[102:103], v[110:111]
	v_pk_add_f32 v[100:101], v[100:101], v[108:109]
	v_pk_add_f32 v[110:111], v[96:97], v[134:135]
	v_mul_f32_e32 v96, v101, v101
	v_mul_f32_e32 v97, v103, v103
	v_fmac_f32_e32 v96, v100, v100
	v_fmac_f32_e32 v97, v102, v102
	v_lshlrev_b32_e32 v136, 16, v139
	v_and_b32_e32 v137, 0xffff0000, v139
	v_add_f32_e32 v96, v96, v97
	v_mul_f32_e32 v97, v111, v111
	v_pk_add_f32 v[108:109], v[98:99], v[136:137]
	v_fmac_f32_e32 v97, v110, v110
	v_add_f32_e32 v96, v97, v96
	v_mul_f32_e32 v97, v109, v109
	v_fmac_f32_e32 v97, v108, v108
	v_add_f32_e32 v96, v97, v96
	v_add_f32_e32 v96, v140, v96
	s_nop 1
	v_mov_b32_e32 v97, v96
	s_nop 1
	v_permlane16_swap_b32_e32 v96, v97
	s_waitcnt lgkmcnt(1)
	v_lshl_add_u64 v[130:131], s[24:25], 0, v[178:179]
	v_lshl_add_u64 v[130:131], v[162:163], 1, v[130:131]
	v_cvt_pk_bf16_f32 v106, v106, v107
	v_cvt_pk_bf16_f32 v107, v132, v133
	s_waitcnt lgkmcnt(0)
	v_add_f32_e32 v96, v96, v97
	s_nop 1
	v_mov_b32_e32 v97, v96
	s_nop 1
	v_permlane32_swap_b32_e32 v96, v97
	global_store_dwordx4 v[130:131], v[104:107], off
	v_cvt_pk_bf16_f32 v98, v100, v101
	v_cvt_pk_bf16_f32 v99, v102, v103
	v_cvt_pk_bf16_f32 v100, v110, v111
	v_cvt_pk_bf16_f32 v101, v108, v109
	global_store_dwordx4 v[130:131], v[98:101], off offset:256
	s_and_saveexec_b64 s[36:37], s[6:7]
	s_cbranch_execz .LBB0_301
	s_waitcnt lgkmcnt(0)
	v_add_f32_e32 v98, v96, v97
	v_lshlrev_b64 v[96:97], 6, v[174:175]
	v_lshl_add_u64 v[96:97], s[26:27], 0, v[96:97]
	v_lshl_add_u64 v[96:97], s[34:35], 2, v[96:97]
	s_lshl_b32 s90, s61, 2
	v_lshl_add_u64 v[96:97], v[96:97], 0, s[90:91]
	global_store_dword v[96:97], v98, off
.LBB0_301:
	s_or_b64 exec, exec, s[36:37]
	v_lshlrev_b32_e32 v98, 16, v124
	v_and_b32_e32 v99, 0xffff0000, v124
	v_lshlrev_b32_e32 v100, 16, v125
	v_and_b32_e32 v101, 0xffff0000, v125
	v_lshlrev_b32_e32 v102, 16, v126
	v_and_b32_e32 v103, 0xffff0000, v126
	v_lshlrev_b32_e32 v104, 16, v127
	v_and_b32_e32 v105, 0xffff0000, v127
	v_pk_add_f32 v[94:95], v[94:95], v[100:101]
	v_pk_add_f32 v[92:93], v[92:93], v[98:99]
	v_pk_add_f32 v[98:99], v[90:91], v[104:105]
	v_pk_add_f32 v[90:91], v[88:89], v[102:103]
	v_mul_f32_e32 v88, v93, v93
	v_mul_f32_e32 v89, v95, v95
	v_fmac_f32_e32 v88, v92, v92
	v_fmac_f32_e32 v89, v94, v94
	v_add_f32_e32 v88, v88, v89
	v_mul_f32_e32 v89, v91, v91
	v_fmac_f32_e32 v89, v90, v90
	v_add_f32_e32 v88, v89, v88
	v_mul_f32_e32 v89, v99, v99
	v_fmac_f32_e32 v89, v98, v98
	v_add_f32_e32 v104, v89, v88
	v_cvt_pk_bf16_f32 v88, v92, v93
	v_cvt_pk_bf16_f32 v89, v94, v95
	v_lshlrev_b32_e32 v92, 16, v120
	v_and_b32_e32 v93, 0xffff0000, v120
	v_lshlrev_b32_e32 v94, 16, v121
	v_and_b32_e32 v95, 0xffff0000, v121
	v_lshlrev_b32_e32 v100, 16, v122
	v_and_b32_e32 v101, 0xffff0000, v122
	v_pk_add_f32 v[86:87], v[86:87], v[94:95]
	v_pk_add_f32 v[84:85], v[84:85], v[92:93]
	v_pk_add_f32 v[94:95], v[80:81], v[100:101]
	v_mul_f32_e32 v80, v85, v85
	v_mul_f32_e32 v81, v87, v87
	v_fmac_f32_e32 v80, v84, v84
	v_fmac_f32_e32 v81, v86, v86
	v_lshlrev_b32_e32 v102, 16, v123
	v_and_b32_e32 v103, 0xffff0000, v123
	v_add_f32_e32 v80, v80, v81
	v_mul_f32_e32 v81, v95, v95
	v_pk_add_f32 v[92:93], v[82:83], v[102:103]
	v_fmac_f32_e32 v81, v94, v94
	v_add_f32_e32 v80, v81, v80
	v_mul_f32_e32 v81, v93, v93
	v_fmac_f32_e32 v81, v92, v92
	v_add_f32_e32 v80, v81, v80
	v_add_f32_e32 v80, v104, v80
	s_nop 1
	v_mov_b32_e32 v81, v80
	s_nop 1
	v_permlane16_swap_b32_e32 v80, v81
	s_waitcnt lgkmcnt(1)
	v_lshl_add_u64 v[96:97], s[24:25], 0, v[176:177]
	v_lshl_add_u64 v[96:97], v[162:163], 1, v[96:97]
	v_cvt_pk_bf16_f32 v90, v90, v91
	v_cvt_pk_bf16_f32 v91, v98, v99
	s_waitcnt lgkmcnt(0)
	v_add_f32_e32 v80, v80, v81
	s_nop 1
	v_mov_b32_e32 v81, v80
	s_nop 1
	v_permlane32_swap_b32_e32 v80, v81
	global_store_dwordx4 v[96:97], v[88:91], off
	v_cvt_pk_bf16_f32 v82, v84, v85
	v_cvt_pk_bf16_f32 v83, v86, v87
	v_cvt_pk_bf16_f32 v84, v94, v95
	v_cvt_pk_bf16_f32 v85, v92, v93
	global_store_dwordx4 v[96:97], v[82:85], off offset:256
	s_and_saveexec_b64 s[36:37], s[6:7]
	s_cbranch_execz .LBB0_303
	s_waitcnt lgkmcnt(0)
	v_add_f32_e32 v82, v80, v81
	v_lshlrev_b64 v[80:81], 6, v[170:171]
	v_lshl_add_u64 v[80:81], s[26:27], 0, v[80:81]
	v_lshl_add_u64 v[80:81], s[34:35], 2, v[80:81]
	s_lshl_b32 s90, s61, 2
	v_lshl_add_u64 v[80:81], v[80:81], 0, s[90:91]
	global_store_dword v[80:81], v82, off
; __device__ __forceinline__ unsigned cvt_pk_bf16(float lo, float hi) { unsigned r; asm volatile("v_cvt_pk_bf16_f32 %0, %1, %2" : "=v"(r) : "v"(lo), "v"(hi)); return r; }
; #define GAS __attribute__((address_space(1)))
;     __device__ __forceinline__ void operator()(const f32x4 (&acc)[2][2][4][2], const Unit& u, int wr, int wc, int fr, int fq) const {
;     ...
;         for (int ai = 0; ai < 2; ++ai) {
;             u32x4 xo[4][2];
; #pragma unroll
;             for (int m = 0; m < 4; ++m)
; #pragma unroll
;                 for (int bj = 0; bj < 2; ++bj) xo[m][bj] = *(const GAS u32x4*)(xb + (size_t)(row0 + ai * 128 + m * 16) * DM + col0 + bj * 128);
;             asm volatile("" ::: "memory");
; #pragma unroll
;             for (int m = 0; m < 4; ++m) {
;                 const int row = row0 + ai * 128 + m * 16; float part = 0.f;
; #pragma unroll
;                 for (int bj = 0; bj < 2; ++bj) {
;                     bf16_t* xp = xb + (size_t)row * DM + col0 + bj * 128;
;                     const u32x4 q = xo[m][bj];
;                     f32x4 x0, x1;
;                     x0[0] = __uint_as_float(q.x << 16); x0[1] = __uint_as_float(q.x & 0xffff0000u); x0[2] = __uint_as_float(q.y << 16); x0[3] = __uint_as_float(q.y & 0xffff0000u);
;                     x1[0] = __uint_as_float(q.z << 16); x1[1] = __uint_as_float(q.z & 0xffff0000u); x1[2] = __uint_as_float(q.w << 16); x1[3] = __uint_as_float(q.w & 0xffff0000u);
;                     x0 = x0 + acc[ai][bj][m][0]; x1 = x1 + acc[ai][bj][m][1];
;                     part += (x0[0] * x0[0] + x0[1] * x0[1]) + (x0[2] * x0[2] + x0[3] * x0[3]) + (x1[0] * x1[0] + x1[1] * x1[1]) + (x1[2] * x1[2] + x1[3] * x1[3]);
;                     u32x4 w; w.x = cvt_pk_bf16(x0[0], x0[1]); w.y = cvt_pk_bf16(x0[2], x0[3]); w.z = cvt_pk_bf16(x1[0], x1[1]); w.w = cvt_pk_bf16(x1[2], x1[3]);
;                     *(GAS u32x4*)xp = w;
;                 }
;                 part += __shfl_xor(part, 16); part += __shfl_xor(part, 32);
;                 if (fq == 0) *(GAS float*)(ssacc + (size_t)row * 16 + u.pn * 4 + wc) = part;
.LBB0_303:
	s_or_b64 exec, exec, s[36:37]
	v_lshlrev_b32_e32 v82, 16, v116
	v_and_b32_e32 v83, 0xffff0000, v116
	v_lshlrev_b32_e32 v84, 16, v117
	v_and_b32_e32 v85, 0xffff0000, v117
	v_lshlrev_b32_e32 v86, 16, v118
	v_and_b32_e32 v87, 0xffff0000, v118
	v_lshlrev_b32_e32 v88, 16, v119
	v_and_b32_e32 v89, 0xffff0000, v119
	v_pk_add_f32 v[78:79], v[78:79], v[84:85]
	v_pk_add_f32 v[76:77], v[76:77], v[82:83]
	v_pk_add_f32 v[82:83], v[74:75], v[88:89]
	v_pk_add_f32 v[74:75], v[72:73], v[86:87]
	v_mul_f32_e32 v72, v77, v77
	v_mul_f32_e32 v73, v79, v79
	v_fmac_f32_e32 v72, v76, v76
	v_fmac_f32_e32 v73, v78, v78
	v_add_f32_e32 v72, v72, v73
	v_mul_f32_e32 v73, v75, v75
	v_fmac_f32_e32 v73, v74, v74
	v_add_f32_e32 v72, v73, v72
	v_mul_f32_e32 v73, v83, v83
	v_fmac_f32_e32 v73, v82, v82
	v_add_f32_e32 v88, v73, v72
	v_cvt_pk_bf16_f32 v72, v76, v77
	v_cvt_pk_bf16_f32 v73, v78, v79
	v_lshlrev_b32_e32 v76, 16, v112
	v_and_b32_e32 v77, 0xffff0000, v112
	v_lshlrev_b32_e32 v78, 16, v113
	v_and_b32_e32 v79, 0xffff0000, v113
	v_lshlrev_b32_e32 v84, 16, v114
	v_and_b32_e32 v85, 0xffff0000, v114
	v_pk_add_f32 v[70:71], v[70:71], v[78:79]
	v_pk_add_f32 v[68:69], v[68:69], v[76:77]
	v_pk_add_f32 v[78:79], v[64:65], v[84:85]
	v_mul_f32_e32 v64, v69, v69
	v_mul_f32_e32 v65, v71, v71
	v_fmac_f32_e32 v64, v68, v68
	v_fmac_f32_e32 v65, v70, v70
	v_lshlrev_b32_e32 v86, 16, v115
	v_and_b32_e32 v87, 0xffff0000, v115
	v_add_f32_e32 v64, v64, v65
	v_mul_f32_e32 v65, v79, v79
	v_pk_add_f32 v[76:77], v[66:67], v[86:87]
	v_fmac_f32_e32 v65, v78, v78
	v_add_f32_e32 v64, v65, v64
	v_mul_f32_e32 v65, v77, v77
	v_fmac_f32_e32 v65, v76, v76
	v_add_f32_e32 v64, v65, v64
	v_add_f32_e32 v64, v88, v64
	s_nop 1
	v_mov_b32_e32 v65, v64
	s_nop 1
	v_permlane16_swap_b32_e32 v64, v65
	s_waitcnt lgkmcnt(1)
	v_lshl_add_u64 v[80:81], s[24:25], 0, v[172:173]
	v_lshl_add_u64 v[80:81], v[162:163], 1, v[80:81]
	v_cvt_pk_bf16_f32 v74, v74, v75
	v_cvt_pk_bf16_f32 v75, v82, v83
	s_waitcnt lgkmcnt(0)
	v_add_f32_e32 v64, v64, v65
	s_nop 1
	v_mov_b32_e32 v65, v64
	s_nop 1
	v_permlane32_swap_b32_e32 v64, v65
	global_store_dwordx4 v[80:81], v[72:75], off
	v_cvt_pk_bf16_f32 v66, v68, v69
	v_cvt_pk_bf16_f32 v67, v70, v71
	v_cvt_pk_bf16_f32 v68, v78, v79
	v_cvt_pk_bf16_f32 v69, v76, v77
	global_store_dwordx4 v[80:81], v[66:69], off offset:256
	s_and_saveexec_b64 s[36:37], s[6:7]
	s_cbranch_execz .LBB0_305
	s_waitcnt lgkmcnt(0)
	v_add_f32_e32 v66, v64, v65
	v_lshlrev_b64 v[64:65], 6, v[168:169]
	v_lshl_add_u64 v[64:65], s[26:27], 0, v[64:65]
	v_lshl_add_u64 v[64:65], s[34:35], 2, v[64:65]
	s_lshl_b32 s90, s61, 2
	v_lshl_add_u64 v[64:65], v[64:65], 0, s[90:91]
	global_store_dword v[64:65], v66, off
.LBB0_305:
	s_or_b64 exec, exec, s[36:37]
	v_add_u32_e32 v104, 0x80, v166
	v_ashrrev_i32_e32 v105, 31, v104
	v_lshlrev_b64 v[106:107], 11, v[104:105]
	s_waitcnt lgkmcnt(0)
	v_lshl_add_u64 v[64:65], v[164:165], 0, v[106:107]
	global_load_dwordx4 v[108:111], v[64:65], off
	global_load_dwordx4 v[88:91], v[64:65], off offset:256
	v_add_u32_e32 v98, 0x90, v166
	v_ashrrev_i32_e32 v99, 31, v98
	v_add_u32_e32 v94, 0xa0, v166
	v_lshlrev_b64 v[102:103], 11, v[98:99]
	v_ashrrev_i32_e32 v95, 31, v94
	v_add_u32_e32 v92, 0xb0, v166
	v_lshl_add_u64 v[64:65], v[164:165], 0, v[102:103]
	v_lshlrev_b64 v[100:101], 11, v[94:95]
	v_ashrrev_i32_e32 v93, 31, v92
	global_load_dwordx4 v[84:87], v[64:65], off
	global_load_dwordx4 v[80:83], v[64:65], off offset:256
	v_lshl_add_u64 v[64:65], v[164:165], 0, v[100:101]
	v_lshlrev_b64 v[96:97], 11, v[92:93]
	global_load_dwordx4 v[76:79], v[64:65], off
	global_load_dwordx4 v[72:75], v[64:65], off offset:256
	v_lshl_add_u64 v[64:65], v[164:165], 0, v[96:97]
	global_load_dwordx4 v[68:71], v[64:65], off
	s_nop 0
	global_load_dwordx4 v[64:67], v[64:65], off offset:256
	v_lshl_add_u64 v[106:107], s[24:25], 0, v[106:107]
	v_lshl_add_u64 v[106:107], v[162:163], 1, v[106:107]
	s_waitcnt vmcnt(7)
	v_lshlrev_b32_e32 v112, 16, v108
	v_and_b32_e32 v113, 0xffff0000, v108
	v_lshlrev_b32_e32 v108, 16, v109
	v_and_b32_e32 v109, 0xffff0000, v109
	v_lshlrev_b32_e32 v114, 16, v110
	v_and_b32_e32 v115, 0xffff0000, v110
	v_lshlrev_b32_e32 v110, 16, v111
	v_and_b32_e32 v111, 0xffff0000, v111
	v_pk_add_f32 v[62:63], v[62:63], v[108:109]
	v_pk_add_f32 v[60:61], v[60:61], v[112:113]
	v_pk_add_f32 v[108:109], v[58:59], v[110:111]
	v_pk_add_f32 v[58:59], v[56:57], v[114:115]
	v_mul_f32_e32 v56, v61, v61
	v_mul_f32_e32 v57, v63, v63
	v_fmac_f32_e32 v56, v60, v60
	v_fmac_f32_e32 v57, v62, v62
	v_add_f32_e32 v56, v56, v57
	v_mul_f32_e32 v57, v59, v59
	v_fmac_f32_e32 v57, v58, v58
	v_add_f32_e32 v56, v57, v56
	v_mul_f32_e32 v57, v109, v109
	v_fmac_f32_e32 v57, v108, v108
	v_add_f32_e32 v110, v57, v56
	v_cvt_pk_bf16_f32 v56, v60, v61
	v_cvt_pk_bf16_f32 v57, v62, v63
	v_cvt_pk_bf16_f32 v58, v58, v59
	v_cvt_pk_bf16_f32 v59, v108, v109
	global_store_dwordx4 v[106:107], v[56:59], off
	s_waitcnt vmcnt(7)
	v_lshlrev_b32_e32 v60, 16, v90
	v_and_b32_e32 v61, 0xffff0000, v90
	v_lshlrev_b32_e32 v56, 16, v88
	v_and_b32_e32 v57, 0xffff0000, v88
	v_lshlrev_b32_e32 v58, 16, v89
	v_and_b32_e32 v59, 0xffff0000, v89
	v_lshlrev_b32_e32 v62, 16, v91
	v_and_b32_e32 v63, 0xffff0000, v91
	v_pk_add_f32 v[54:55], v[54:55], v[58:59]
	v_pk_add_f32 v[52:53], v[52:53], v[56:57]
	v_pk_add_f32 v[56:57], v[50:51], v[62:63]
	v_pk_add_f32 v[50:51], v[48:49], v[60:61]
	v_mul_f32_e32 v48, v53, v53
	v_mul_f32_e32 v49, v55, v55
	v_fmac_f32_e32 v48, v52, v52
	v_fmac_f32_e32 v49, v54, v54
	v_add_f32_e32 v48, v48, v49
	v_mul_f32_e32 v49, v51, v51
	v_fmac_f32_e32 v49, v50, v50
	v_add_f32_e32 v48, v49, v48
	v_mul_f32_e32 v49, v57, v57
	v_fmac_f32_e32 v49, v56, v56
	v_add_f32_e32 v48, v49, v48
	v_add_f32_e32 v58, v110, v48
	v_cvt_pk_bf16_f32 v48, v52, v53
	v_cvt_pk_bf16_f32 v49, v54, v55
	v_cvt_pk_bf16_f32 v50, v50, v51
	v_cvt_pk_bf16_f32 v51, v56, v57
	global_store_dwordx4 v[106:107], v[48:51], off offset:256
	s_nop 1
	v_mov_b32_e32 v48, v58
	s_nop 1
	v_permlane16_swap_b32_e32 v58, v48
	s_waitcnt lgkmcnt(0)
	v_add_f32_e32 v48, v58, v48
	s_nop 1
	v_mov_b32_e32 v49, v48
	s_nop 1
	v_permlane32_swap_b32_e32 v48, v49
	s_and_saveexec_b64 s[36:37], s[6:7]
	s_cbranch_execz .LBB0_307
	s_waitcnt lgkmcnt(0)
	v_add_f32_e32 v50, v48, v49
	v_lshlrev_b64 v[48:49], 6, v[104:105]
	v_lshl_add_u64 v[48:49], s[26:27], 0, v[48:49]
	v_lshl_add_u64 v[48:49], s[34:35], 2, v[48:49]
	s_lshl_b32 s90, s61, 2
	v_lshl_add_u64 v[48:49], v[48:49], 0, s[90:91]
	global_store_dword v[48:49], v50, off
; __device__ __forceinline__ unsigned cvt_pk_bf16(float lo, float hi) { unsigned r; asm volatile("v_cvt_pk_bf16_f32 %0, %1, %2" : "=v"(r) : "v"(lo), "v"(hi)); return r; }
; #define GAS __attribute__((address_space(1)))
;     __device__ __forceinline__ void operator()(const f32x4 (&acc)[2][2][4][2], const Unit& u, int wr, int wc, int fr, int fq) const {
;     ...
;         for (int ai = 0; ai < 2; ++ai) {
;             u32x4 xo[4][2];
; #pragma unroll
;             for (int m = 0; m < 4; ++m)
; #pragma unroll
;                 for (int bj = 0; bj < 2; ++bj) xo[m][bj] = *(const GAS u32x4*)(xb + (size_t)(row0 + ai * 128 + m * 16) * DM + col0 + bj * 128);
;             asm volatile("" ::: "memory");
; #pragma unroll
;             for (int m = 0; m < 4; ++m) {
;                 const int row = row0 + ai * 128 + m * 16; float part = 0.f;
; #pragma unroll
;                 for (int bj = 0; bj < 2; ++bj) {
;                     bf16_t* xp = xb + (size_t)row * DM + col0 + bj * 128;
;                     const u32x4 q = xo[m][bj];
;                     f32x4 x0, x1;
;                     x0[0] = __uint_as_float(q.x << 16); x0[1] = __uint_as_float(q.x & 0xffff0000u); x0[2] = __uint_as_float(q.y << 16); x0[3] = __uint_as_float(q.y & 0xffff0000u);
;                     x1[0] = __uint_as_float(q.z << 16); x1[1] = __uint_as_float(q.z & 0xffff0000u); x1[2] = __uint_as_float(q.w << 16); x1[3] = __uint_as_float(q.w & 0xffff0000u);
;                     x0 = x0 + acc[ai][bj][m][0]; x1 = x1 + acc[ai][bj][m][1];
;                     part += (x0[0] * x0[0] + x0[1] * x0[1]) + (x0[2] * x0[2] + x0[3] * x0[3]) + (x1[0] * x1[0] + x1[1] * x1[1]) + (x1[2] * x1[2] + x1[3] * x1[3]);
;                     u32x4 w; w.x = cvt_pk_bf16(x0[0], x0[1]); w.y = cvt_pk_bf16(x0[2], x0[3]); w.z = cvt_pk_bf16(x1[0], x1[1]); w.w = cvt_pk_bf16(x1[2], x1[3]);
;                     *(GAS u32x4*)xp = w;
;                 }
;                 part += __shfl_xor(part, 16); part += __shfl_xor(part, 32);
;                 if (fq == 0) *(GAS float*)(ssacc + (size_t)row * 16 + u.pn * 4 + wc) = part;
.LBB0_307:
	s_or_b64 exec, exec, s[36:37]
	s_waitcnt vmcnt(7)
	v_lshlrev_b32_e32 v50, 16, v84
	v_and_b32_e32 v51, 0xffff0000, v84
	v_lshlrev_b32_e32 v52, 16, v85
	v_and_b32_e32 v53, 0xffff0000, v85
	v_lshlrev_b32_e32 v54, 16, v86
	v_and_b32_e32 v55, 0xffff0000, v86
	v_lshlrev_b32_e32 v56, 16, v87
	v_and_b32_e32 v57, 0xffff0000, v87
	v_pk_add_f32 v[46:47], v[46:47], v[52:53]
	v_pk_add_f32 v[44:45], v[44:45], v[50:51]
	v_pk_add_f32 v[50:51], v[42:43], v[56:57]
	v_pk_add_f32 v[42:43], v[40:41], v[54:55]
	v_mul_f32_e32 v40, v45, v45
	v_mul_f32_e32 v41, v47, v47
	v_fmac_f32_e32 v40, v44, v44
	v_fmac_f32_e32 v41, v46, v46
	v_add_f32_e32 v40, v40, v41
	v_mul_f32_e32 v41, v43, v43
	v_fmac_f32_e32 v41, v42, v42
	v_add_f32_e32 v40, v41, v40
	v_mul_f32_e32 v41, v51, v51
	v_fmac_f32_e32 v41, v50, v50
	v_add_f32_e32 v56, v41, v40
	v_cvt_pk_bf16_f32 v40, v44, v45
	v_cvt_pk_bf16_f32 v41, v46, v47
	s_waitcnt vmcnt(6)
	v_lshlrev_b32_e32 v44, 16, v80
	v_and_b32_e32 v45, 0xffff0000, v80
	v_lshlrev_b32_e32 v46, 16, v81
	v_and_b32_e32 v47, 0xffff0000, v81
	v_lshlrev_b32_e32 v52, 16, v82
	v_and_b32_e32 v53, 0xffff0000, v82
	v_pk_add_f32 v[38:39], v[38:39], v[46:47]
	v_pk_add_f32 v[36:37], v[36:37], v[44:45]
	v_pk_add_f32 v[46:47], v[32:33], v[52:53]
	v_mul_f32_e32 v32, v37, v37
	v_mul_f32_e32 v33, v39, v39
	v_fmac_f32_e32 v32, v36, v36
	v_fmac_f32_e32 v33, v38, v38
	v_lshlrev_b32_e32 v54, 16, v83
	v_and_b32_e32 v55, 0xffff0000, v83
	v_add_f32_e32 v32, v32, v33
	v_mul_f32_e32 v33, v47, v47
	v_pk_add_f32 v[44:45], v[34:35], v[54:55]
	v_fmac_f32_e32 v33, v46, v46
	v_add_f32_e32 v32, v33, v32
	v_mul_f32_e32 v33, v45, v45
	v_fmac_f32_e32 v33, v44, v44
	v_add_f32_e32 v32, v33, v32
	v_add_f32_e32 v32, v56, v32
	s_nop 1
	v_mov_b32_e32 v33, v32
	s_nop 1
	v_permlane16_swap_b32_e32 v32, v33
	s_waitcnt lgkmcnt(1)
	v_lshl_add_u64 v[48:49], s[24:25], 0, v[102:103]
	v_lshl_add_u64 v[48:49], v[162:163], 1, v[48:49]
	v_cvt_pk_bf16_f32 v42, v42, v43
	v_cvt_pk_bf16_f32 v43, v50, v51
	s_waitcnt lgkmcnt(0)
	v_add_f32_e32 v32, v32, v33
	s_nop 1
	v_mov_b32_e32 v33, v32
	s_nop 1
	v_permlane32_swap_b32_e32 v32, v33
	global_store_dwordx4 v[48:49], v[40:43], off
	v_cvt_pk_bf16_f32 v34, v36, v37
	v_cvt_pk_bf16_f32 v35, v38, v39
	v_cvt_pk_bf16_f32 v36, v46, v47
	v_cvt_pk_bf16_f32 v37, v44, v45
	global_store_dwordx4 v[48:49], v[34:37], off offset:256
	s_and_saveexec_b64 s[36:37], s[6:7]
	s_cbranch_execz .LBB0_309
	s_waitcnt lgkmcnt(0)
	v_add_f32_e32 v34, v32, v33
	v_lshlrev_b64 v[32:33], 6, v[98:99]
	v_lshl_add_u64 v[32:33], s[26:27], 0, v[32:33]
	v_lshl_add_u64 v[32:33], s[34:35], 2, v[32:33]
	s_lshl_b32 s90, s61, 2
	v_lshl_add_u64 v[32:33], v[32:33], 0, s[90:91]
	global_store_dword v[32:33], v34, off
; __device__ __forceinline__ unsigned cvt_pk_bf16(float lo, float hi) { unsigned r; asm volatile("v_cvt_pk_bf16_f32 %0, %1, %2" : "=v"(r) : "v"(lo), "v"(hi)); return r; }
; #define GAS __attribute__((address_space(1)))
;     __device__ __forceinline__ void operator()(const f32x4 (&acc)[2][2][4][2], const Unit& u, int wr, int wc, int fr, int fq) const {
;     ...
;         for (int ai = 0; ai < 2; ++ai) {
;             u32x4 xo[4][2];
; #pragma unroll
;             for (int m = 0; m < 4; ++m)
; #pragma unroll
;                 for (int bj = 0; bj < 2; ++bj) xo[m][bj] = *(const GAS u32x4*)(xb + (size_t)(row0 + ai * 128 + m * 16) * DM + col0 + bj * 128);
;             asm volatile("" ::: "memory");
; #pragma unroll
;             for (int m = 0; m < 4; ++m) {
;                 const int row = row0 + ai * 128 + m * 16; float part = 0.f;
; #pragma unroll
;                 for (int bj = 0; bj < 2; ++bj) {
;                     bf16_t* xp = xb + (size_t)row * DM + col0 + bj * 128;
;                     const u32x4 q = xo[m][bj];
;                     f32x4 x0, x1;
;                     x0[0] = __uint_as_float(q.x << 16); x0[1] = __uint_as_float(q.x & 0xffff0000u); x0[2] = __uint_as_float(q.y << 16); x0[3] = __uint_as_float(q.y & 0xffff0000u);
;                     x1[0] = __uint_as_float(q.z << 16); x1[1] = __uint_as_float(q.z & 0xffff0000u); x1[2] = __uint_as_float(q.w << 16); x1[3] = __uint_as_float(q.w & 0xffff0000u);
;                     x0 = x0 + acc[ai][bj][m][0]; x1 = x1 + acc[ai][bj][m][1];
;                     part += (x0[0] * x0[0] + x0[1] * x0[1]) + (x0[2] * x0[2] + x0[3] * x0[3]) + (x1[0] * x1[0] + x1[1] * x1[1]) + (x1[2] * x1[2] + x1[3] * x1[3]);
;                     u32x4 w; w.x = cvt_pk_bf16(x0[0], x0[1]); w.y = cvt_pk_bf16(x0[2], x0[3]); w.z = cvt_pk_bf16(x1[0], x1[1]); w.w = cvt_pk_bf16(x1[2], x1[3]);
;                     *(GAS u32x4*)xp = w;
;                 }
;                 part += __shfl_xor(part, 16); part += __shfl_xor(part, 32);
;                 if (fq == 0) *(GAS float*)(ssacc + (size_t)row * 16 + u.pn * 4 + wc) = part;
.LBB0_309:
	s_or_b64 exec, exec, s[36:37]
	s_waitcnt vmcnt(7)
	v_lshlrev_b32_e32 v34, 16, v76
	v_and_b32_e32 v35, 0xffff0000, v76
	v_lshlrev_b32_e32 v36, 16, v77
	v_and_b32_e32 v37, 0xffff0000, v77
	v_lshlrev_b32_e32 v38, 16, v78
	v_and_b32_e32 v39, 0xffff0000, v78
	v_lshlrev_b32_e32 v40, 16, v79
	v_and_b32_e32 v41, 0xffff0000, v79
	v_pk_add_f32 v[30:31], v[30:31], v[36:37]
	v_pk_add_f32 v[28:29], v[28:29], v[34:35]
	v_pk_add_f32 v[34:35], v[26:27], v[40:41]
	v_pk_add_f32 v[26:27], v[24:25], v[38:39]
	v_mul_f32_e32 v24, v29, v29
	v_mul_f32_e32 v25, v31, v31
	v_fmac_f32_e32 v24, v28, v28
	v_fmac_f32_e32 v25, v30, v30
	v_add_f32_e32 v24, v24, v25
	v_mul_f32_e32 v25, v27, v27
	v_fmac_f32_e32 v25, v26, v26
	v_add_f32_e32 v24, v25, v24
	v_mul_f32_e32 v25, v35, v35
	v_fmac_f32_e32 v25, v34, v34
	v_add_f32_e32 v40, v25, v24
	v_cvt_pk_bf16_f32 v24, v28, v29
	v_cvt_pk_bf16_f32 v25, v30, v31
	s_waitcnt vmcnt(6)
	v_lshlrev_b32_e32 v28, 16, v72
	v_and_b32_e32 v29, 0xffff0000, v72
	v_lshlrev_b32_e32 v30, 16, v73
	v_and_b32_e32 v31, 0xffff0000, v73
	v_lshlrev_b32_e32 v36, 16, v74
	v_and_b32_e32 v37, 0xffff0000, v74
	v_pk_add_f32 v[22:23], v[22:23], v[30:31]
	v_pk_add_f32 v[20:21], v[20:21], v[28:29]
	v_pk_add_f32 v[30:31], v[16:17], v[36:37]
	v_mul_f32_e32 v16, v21, v21
	v_mul_f32_e32 v17, v23, v23
	v_fmac_f32_e32 v16, v20, v20
	v_fmac_f32_e32 v17, v22, v22
	v_lshlrev_b32_e32 v38, 16, v75
	v_and_b32_e32 v39, 0xffff0000, v75
	v_add_f32_e32 v16, v16, v17
	v_mul_f32_e32 v17, v31, v31
	v_pk_add_f32 v[28:29], v[18:19], v[38:39]
	v_fmac_f32_e32 v17, v30, v30
	v_add_f32_e32 v16, v17, v16
	v_mul_f32_e32 v17, v29, v29
	v_fmac_f32_e32 v17, v28, v28
	v_add_f32_e32 v16, v17, v16
	v_add_f32_e32 v16, v40, v16
	s_nop 1
	v_mov_b32_e32 v17, v16
	s_nop 1
	v_permlane16_swap_b32_e32 v16, v17
	s_waitcnt lgkmcnt(1)
	v_lshl_add_u64 v[32:33], s[24:25], 0, v[100:101]
	v_lshl_add_u64 v[32:33], v[162:163], 1, v[32:33]
	v_cvt_pk_bf16_f32 v26, v26, v27
	v_cvt_pk_bf16_f32 v27, v34, v35
	s_waitcnt lgkmcnt(0)
	v_add_f32_e32 v16, v16, v17
	s_nop 1
	v_mov_b32_e32 v17, v16
	s_nop 1
	v_permlane32_swap_b32_e32 v16, v17
	global_store_dwordx4 v[32:33], v[24:27], off
	v_cvt_pk_bf16_f32 v18, v20, v21
	v_cvt_pk_bf16_f32 v19, v22, v23
	v_cvt_pk_bf16_f32 v20, v30, v31
	v_cvt_pk_bf16_f32 v21, v28, v29
	global_store_dwordx4 v[32:33], v[18:21], off offset:256
	s_and_saveexec_b64 s[36:37], s[6:7]
	s_cbranch_execz .LBB0_311
	s_waitcnt lgkmcnt(0)
	v_add_f32_e32 v18, v16, v17
	v_lshlrev_b64 v[16:17], 6, v[94:95]
	v_lshl_add_u64 v[16:17], s[26:27], 0, v[16:17]
	v_lshl_add_u64 v[16:17], s[34:35], 2, v[16:17]
	s_lshl_b32 s90, s61, 2
	v_lshl_add_u64 v[16:17], v[16:17], 0, s[90:91]
	global_store_dword v[16:17], v18, off
.LBB0_311:
	s_or_b64 exec, exec, s[36:37]
	s_waitcnt vmcnt(7)
	v_lshlrev_b32_e32 v18, 16, v68
	v_and_b32_e32 v19, 0xffff0000, v68
	v_lshlrev_b32_e32 v20, 16, v69
	v_and_b32_e32 v21, 0xffff0000, v69
	v_lshlrev_b32_e32 v22, 16, v70
	v_and_b32_e32 v23, 0xffff0000, v70
	v_lshlrev_b32_e32 v24, 16, v71
	v_and_b32_e32 v25, 0xffff0000, v71
	v_pk_add_f32 v[14:15], v[14:15], v[20:21]
	v_pk_add_f32 v[12:13], v[12:13], v[18:19]
	v_pk_add_f32 v[18:19], v[10:11], v[24:25]
	v_pk_add_f32 v[10:11], v[8:9], v[22:23]
	v_mul_f32_e32 v8, v13, v13
	v_mul_f32_e32 v9, v15, v15
	v_fmac_f32_e32 v8, v12, v12
	v_fmac_f32_e32 v9, v14, v14
	v_add_f32_e32 v8, v8, v9
	v_mul_f32_e32 v9, v11, v11
	v_fmac_f32_e32 v9, v10, v10
	v_add_f32_e32 v8, v9, v8
	v_mul_f32_e32 v9, v19, v19
	v_fmac_f32_e32 v9, v18, v18
	v_add_f32_e32 v24, v9, v8
	v_cvt_pk_bf16_f32 v8, v12, v13
	v_cvt_pk_bf16_f32 v9, v14, v15
	s_waitcnt vmcnt(6)
	v_lshlrev_b32_e32 v12, 16, v64
	v_and_b32_e32 v13, 0xffff0000, v64
	v_lshlrev_b32_e32 v14, 16, v65
	v_and_b32_e32 v15, 0xffff0000, v65
	v_lshlrev_b32_e32 v20, 16, v66
	v_and_b32_e32 v21, 0xffff0000, v66
	v_pk_add_f32 v[6:7], v[6:7], v[14:15]
	v_pk_add_f32 v[4:5], v[4:5], v[12:13]
	v_pk_add_f32 v[14:15], v[0:1], v[20:21]
	v_mul_f32_e32 v0, v5, v5
	v_mul_f32_e32 v1, v7, v7
	v_fmac_f32_e32 v0, v4, v4
	v_fmac_f32_e32 v1, v6, v6
	v_lshlrev_b32_e32 v22, 16, v67
	v_and_b32_e32 v23, 0xffff0000, v67
	v_add_f32_e32 v0, v0, v1
	v_mul_f32_e32 v1, v15, v15
	v_pk_add_f32 v[12:13], v[2:3], v[22:23]
	v_fmac_f32_e32 v1, v14, v14
	v_add_f32_e32 v0, v1, v0
	v_mul_f32_e32 v1, v13, v13
	v_fmac_f32_e32 v1, v12, v12
	v_add_f32_e32 v0, v1, v0
	v_add_f32_e32 v0, v24, v0
	s_nop 1
	v_mov_b32_e32 v1, v0
	s_nop 1
	v_permlane16_swap_b32_e32 v0, v1
	s_waitcnt lgkmcnt(1)
	v_lshl_add_u64 v[16:17], s[24:25], 0, v[96:97]
	v_lshl_add_u64 v[16:17], v[162:163], 1, v[16:17]
	v_cvt_pk_bf16_f32 v10, v10, v11
	v_cvt_pk_bf16_f32 v11, v18, v19
	s_waitcnt lgkmcnt(0)
	v_add_f32_e32 v0, v0, v1
	s_nop 1
	v_mov_b32_e32 v1, v0
	s_nop 1
	v_permlane32_swap_b32_e32 v0, v1
	global_store_dwordx4 v[16:17], v[8:11], off
	v_cvt_pk_bf16_f32 v2, v4, v5
	v_cvt_pk_bf16_f32 v3, v6, v7
	v_cvt_pk_bf16_f32 v4, v14, v15
	v_cvt_pk_bf16_f32 v5, v12, v13
	global_store_dwordx4 v[16:17], v[2:5], off offset:256
	s_and_saveexec_b64 s[36:37], s[6:7]
	s_cbranch_execz .LBB0_313
	s_waitcnt lgkmcnt(0)
	v_add_f32_e32 v2, v0, v1
	v_lshlrev_b64 v[0:1], 6, v[92:93]
	v_lshl_add_u64 v[0:1], s[26:27], 0, v[0:1]
	v_lshl_add_u64 v[0:1], s[34:35], 2, v[0:1]
	s_lshl_b32 s90, s61, 2
	v_lshl_add_u64 v[0:1], v[0:1], 0, s[90:91]
	global_store_dword v[0:1], v2, off
